# GEMM K-loops: MFMAs of a k-group reordered so four consecutive ones share the first source operand
# baseline (speedup 1.0000x reference)
; #define PG8_STAGE(bufoff, gbase, voff) do { _Pragma("unroll") for (int _i = 0; _i < 2; ++_i) \
;         __builtin_amdgcn_global_load_lds((const unsigned*)((const char*)(gbase) + (voff)[_i]), (PG8_LAS unsigned*)(lds + (bufoff) + ldsw + _i * 8192), 16, 0, 0); } while (0)
; #define PG8_LDA(dst, b, h) do { _Pragma("unroll") for (int m = 0; m < 4; ++m) _Pragma("unroll") for (int k = 0; k < 2; ++k) dst[m][k] = *(const PG8_LAS bf16x8*)(lds + PG8_SA(b, h) + aoff + m * 2048 + k * 1024); } while (0)
; #define PG8_LDB(dst, b, h) do { _Pragma("unroll") for (int n = 0; n < 2; ++n) _Pragma("unroll") for (int k = 0; k < 2; ++k) dst[n][k] = *(const PG8_LAS bf16x8*)(lds + PG8_SB(b, h) + boff + n * 2048 + k * 1024); } while (0)
; #define PG8_MMA(ai, bj, At, Bt) do { __builtin_amdgcn_s_setprio(1); _Pragma("unroll") for (int m = 0; m < 4; ++m) _Pragma("unroll") for (int n = 0; n < 2; ++n) _Pragma("unroll") for (int k = 0; k < 2; ++k) \
;         acc[ai][bj][m][n] = __builtin_amdgcn_mfma_f32_16x16x32_bf16(Bt[n][k], At[m][k], acc[ai][bj][m][n], 0, 0, 0); __builtin_amdgcn_s_setprio(0); } while (0)
; #define PG8_WAIT_V(n) asm volatile("s_waitcnt vmcnt(" #n ")" ::: "memory")
; #define PG8_WAIT_L(n) asm volatile("s_waitcnt lgkmcnt(" #n ")" ::: "memory")
; template <class Epi, class Sched, bool ALIGN_EPI = false, bool SP2 = false>
; __device__ __forceinline__ void gemm_phase(PG8_LAS unsigned char* lds, const Gemm g, const Sched& S, const Epi& E) {
;     ...
;             const bool last = (t == nt - 2);
;             const char* a1 = cA + (size_t)(t + 1) * kstep;
;             const char* a2 = last ? nA : cA + (size_t)(t + 2) * kstep; const char* b2 = last ? nB : cB + (size_t)(t + 2) * kstep;
;             const char* a3 = a2 + kstep; const char* b3 = b2 + kstep;
;             if (last && has_next) S.a_ready(nxt);
;             if constexpr (SP2) {
;             PG8_LDB(B0, 0, 0); PG8_LDB(B1, 0, 1); PG8_SCHED; PG8_LDA(At, 0, 0); PG8_STAGE(PG8_SA(1, 1), a1 + hstep, voffA);
;             PG8_WAIT_V(8); PG8_WAIT_L(0); PG8_BAR; PG8_MMA(0, 0, At, B0); PG8_MMA(0, 1, At, B1); PG8_BAR; PG8_SCHED;
;             PG8_LDA(At, 0, 1); PG8_STAGE(PG8_SB(0, 0), b2, voffB); PG8_STAGE(PG8_SB(0, 1), b2 + hstep, voffB); PG8_STAGE(PG8_SA(0, 0), a2, voffA);
;             PG8_WAIT_V(8); PG8_WAIT_L(0); PG8_BAR; PG8_MMA(1, 0, At, B0); PG8_MMA(1, 1, At, B1); PG8_BAR; PG8_SCHED;
.LBB0_132:
	s_add_u32 s18, s46, 0xfffc0080
	s_addc_u32 s38, s47, -1
	s_add_i32 s39, 0, 0x10000
	s_cmp_eq_u32 s85, 12
	s_cselect_b32 s81, s33, s38
	s_cselect_b32 s80, s73, s18
	v_add_u32_e32 v0, s39, v176
	s_cselect_b32 s45, s75, s84
	s_cselect_b32 s44, s82, s83
	s_add_i32 s18, 0, 0x14000
	ds_read_b128 v[144:147], v0
	ds_read_b128 v[148:151], v0 offset:1024
	ds_read_b128 v[152:155], v0 offset:2048
	ds_read_b128 v[156:159], v0 offset:3072
	v_add_u32_e32 v0, s18, v176
	ds_read_b128 v[160:163], v0
	ds_read_b128 v[164:167], v0 offset:1024
	ds_read_b128 v[168:171], v0 offset:2048
	ds_read_b128 v[172:175], v0 offset:3072
	v_lshl_add_u64 v[218:219], s[46:47], 0, v[140:141]
	s_add_i32 m0, s92, 0xc000
	ds_read_b128 v[180:183], v178
	ds_read_b128 v[184:187], v178 offset:1024
	ds_read_b128 v[188:191], v178 offset:2048
	ds_read_b128 v[192:195], v178 offset:3072
	ds_read_b128 v[202:205], v178 offset:4096
	ds_read_b128 v[206:209], v178 offset:5120
	ds_read_b128 v[210:213], v178 offset:6144
	ds_read_b128 v[214:217], v178 offset:7168
	global_load_lds_dwordx4 v[218:219], off
	v_lshl_add_u64 v[218:219], s[46:47], 0, v[142:143]
	s_add_i32 m0, s92, 0xe000
	s_nop 0
	global_load_lds_dwordx4 v[218:219], off
	s_waitcnt vmcnt(8)
	s_waitcnt lgkmcnt(0)
	s_barrier
	s_setprio 1
	s_waitcnt lgkmcnt(0)
	v_mfma_f32_16x16x32_bf16 v[118:121], v[144:147], v[180:183], v[118:121]
	v_mfma_f32_16x16x32_bf16 v[102:105], v[144:147], v[188:191], v[102:105]
	v_mfma_f32_16x16x32_bf16 v[86:89], v[144:147], v[202:205], v[86:89]
	v_mfma_f32_16x16x32_bf16 v[70:73], v[144:147], v[210:213], v[70:73]
	v_mfma_f32_16x16x32_bf16 v[114:117], v[152:155], v[180:183], v[114:117]
	v_mfma_f32_16x16x32_bf16 v[98:101], v[152:155], v[188:191], v[98:101]
	v_mfma_f32_16x16x32_bf16 v[82:85], v[152:155], v[202:205], v[82:85]
	v_mfma_f32_16x16x32_bf16 v[66:69], v[152:155], v[210:213], v[66:69]
	v_mfma_f32_16x16x32_bf16 v[118:121], v[148:151], v[184:187], v[118:121]
	v_mfma_f32_16x16x32_bf16 v[102:105], v[148:151], v[192:195], v[102:105]
	v_mfma_f32_16x16x32_bf16 v[86:89], v[148:151], v[206:209], v[86:89]
	v_mfma_f32_16x16x32_bf16 v[70:73], v[148:151], v[214:217], v[70:73]
	v_mfma_f32_16x16x32_bf16 v[114:117], v[156:159], v[184:187], v[114:117]
	v_mfma_f32_16x16x32_bf16 v[98:101], v[156:159], v[192:195], v[98:101]
	v_mfma_f32_16x16x32_bf16 v[82:85], v[156:159], v[206:209], v[82:85]
	v_mfma_f32_16x16x32_bf16 v[66:69], v[156:159], v[214:217], v[66:69]
	s_setprio 0
	s_setprio 1
	v_mfma_f32_16x16x32_bf16 v[126:129], v[160:163], v[180:183], v[126:129]
	v_mfma_f32_16x16x32_bf16 v[110:113], v[160:163], v[188:191], v[110:113]
	v_mfma_f32_16x16x32_bf16 v[94:97], v[160:163], v[202:205], v[94:97]
	v_mfma_f32_16x16x32_bf16 v[78:81], v[160:163], v[210:213], v[78:81]
	v_mfma_f32_16x16x32_bf16 v[122:125], v[168:171], v[180:183], v[122:125]
	v_mfma_f32_16x16x32_bf16 v[106:109], v[168:171], v[188:191], v[106:109]
	v_mfma_f32_16x16x32_bf16 v[90:93], v[168:171], v[202:205], v[90:93]
	v_mfma_f32_16x16x32_bf16 v[74:77], v[168:171], v[210:213], v[74:77]
	v_mfma_f32_16x16x32_bf16 v[126:129], v[164:167], v[184:187], v[126:129]
	v_mfma_f32_16x16x32_bf16 v[110:113], v[164:167], v[192:195], v[110:113]
	v_mfma_f32_16x16x32_bf16 v[94:97], v[164:167], v[206:209], v[94:97]
	v_mfma_f32_16x16x32_bf16 v[78:81], v[164:167], v[214:217], v[78:81]
	v_mfma_f32_16x16x32_bf16 v[122:125], v[172:175], v[184:187], v[122:125]
	v_mfma_f32_16x16x32_bf16 v[106:109], v[172:175], v[192:195], v[106:109]
	v_mfma_f32_16x16x32_bf16 v[90:93], v[172:175], v[206:209], v[90:93]
	v_mfma_f32_16x16x32_bf16 v[74:77], v[172:175], v[214:217], v[74:77]
	s_setprio 0
	s_barrier
	s_add_i32 s38, s39, s91
	v_lshl_add_u64 v[218:219], s[44:45], 0, v[134:135]
	s_mov_b32 m0, s38
	ds_read_b128 v[180:183], v178 offset:16384
	ds_read_b128 v[184:187], v178 offset:17408
	ds_read_b128 v[188:191], v178 offset:18432
	ds_read_b128 v[192:195], v178 offset:19456
	ds_read_b128 v[202:205], v178 offset:20480
	ds_read_b128 v[206:209], v178 offset:21504
	ds_read_b128 v[210:213], v178 offset:22528
	ds_read_b128 v[214:217], v178 offset:23552
	global_load_lds_dwordx4 v[218:219], off
	s_add_i32 m0, s38, 0x2000
	s_add_u32 s38, s44, 0x40000
	v_lshl_add_u64 v[220:221], s[44:45], 0, v[130:131]
	s_addc_u32 s39, s45, 0
	s_add_i32 s18, s18, s91
	global_load_lds_dwordx4 v[220:221], off
	v_lshl_add_u64 v[222:223], s[38:39], 0, v[134:135]
	s_mov_b32 m0, s18
	v_lshl_add_u64 v[224:225], s[80:81], 0, v[132:133]
	global_load_lds_dwordx4 v[222:223], off
	v_lshl_add_u64 v[222:223], s[38:39], 0, v[130:131]
	s_add_i32 m0, s18, 0x2000
	s_nop 0
	global_load_lds_dwordx4 v[222:223], off
	v_lshl_add_u64 v[222:223], s[80:81], 0, v[136:137]
	s_mov_b32 m0, s92
	s_nop 0
	global_load_lds_dwordx4 v[222:223], off
	s_mov_b32 m0, s93
	s_nop 0
	global_load_lds_dwordx4 v[224:225], off
	s_waitcnt vmcnt(8)
	s_waitcnt lgkmcnt(0)
	s_barrier
; #define PG8_STAGE(bufoff, gbase, voff) do { _Pragma("unroll") for (int _i = 0; _i < 2; ++_i) \
;         __builtin_amdgcn_global_load_lds((const unsigned*)((const char*)(gbase) + (voff)[_i]), (PG8_LAS unsigned*)(lds + (bufoff) + ldsw + _i * 8192), 16, 0, 0); } while (0)
; #define PG8_LDA(dst, b, h) do { _Pragma("unroll") for (int m = 0; m < 4; ++m) _Pragma("unroll") for (int k = 0; k < 2; ++k) dst[m][k] = *(const PG8_LAS bf16x8*)(lds + PG8_SA(b, h) + aoff + m * 2048 + k * 1024); } while (0)
; #define PG8_LDB(dst, b, h) do { _Pragma("unroll") for (int n = 0; n < 2; ++n) _Pragma("unroll") for (int k = 0; k < 2; ++k) dst[n][k] = *(const PG8_LAS bf16x8*)(lds + PG8_SB(b, h) + boff + n * 2048 + k * 1024); } while (0)
; #define PG8_MMA(ai, bj, At, Bt) do { __builtin_amdgcn_s_setprio(1); _Pragma("unroll") for (int m = 0; m < 4; ++m) _Pragma("unroll") for (int n = 0; n < 2; ++n) _Pragma("unroll") for (int k = 0; k < 2; ++k) \
;         acc[ai][bj][m][n] = __builtin_amdgcn_mfma_f32_16x16x32_bf16(Bt[n][k], At[m][k], acc[ai][bj][m][n], 0, 0, 0); __builtin_amdgcn_s_setprio(0); } while (0)
; #define PG8_WAIT_V(n) asm volatile("s_waitcnt vmcnt(" #n ")" ::: "memory")
; #define PG8_WAIT_L(n) asm volatile("s_waitcnt lgkmcnt(" #n ")" ::: "memory")
; #define PG8_BAR __builtin_amdgcn_s_barrier()
; #define PG8_SCHED __builtin_amdgcn_sched_barrier(0)
; template <class Epi, class Sched, bool ALIGN_EPI = false, bool SP2 = false>
; __device__ __forceinline__ void gemm_phase(PG8_LAS unsigned char* lds, const Gemm g, const Sched& S, const Epi& E) {
;     ...
;             PG8_WAIT_V(8); PG8_WAIT_L(0); PG8_BAR; PG8_MMA(1, 0, At, B0); PG8_MMA(1, 1, At, B1); PG8_BAR; PG8_SCHED;
;             PG8_LDB(B0, 1, 0); PG8_LDB(B1, 1, 1); PG8_SCHED; PG8_LDA(At, 1, 0); PG8_STAGE(PG8_SA(0, 1), a2 + hstep, voffA);
;             PG8_WAIT_V(8); PG8_WAIT_L(0); PG8_BAR; PG8_MMA(0, 0, At, B0); PG8_MMA(0, 1, At, B1); PG8_BAR; PG8_SCHED;
	s_setprio 1
	s_waitcnt lgkmcnt(0)
	v_mfma_f32_16x16x32_bf16 v[54:57], v[144:147], v[180:183], v[54:57]
	v_mfma_f32_16x16x32_bf16 v[38:41], v[144:147], v[188:191], v[38:41]
	v_mfma_f32_16x16x32_bf16 v[22:25], v[144:147], v[202:205], v[22:25]
	v_mfma_f32_16x16x32_bf16 v[6:9], v[144:147], v[210:213], v[6:9]
	v_mfma_f32_16x16x32_bf16 v[50:53], v[152:155], v[180:183], v[50:53]
	v_mfma_f32_16x16x32_bf16 v[34:37], v[152:155], v[188:191], v[34:37]
	v_mfma_f32_16x16x32_bf16 v[18:21], v[152:155], v[202:205], v[18:21]
	v_mfma_f32_16x16x32_bf16 v[2:5], v[152:155], v[210:213], v[2:5]
	v_mfma_f32_16x16x32_bf16 v[54:57], v[148:151], v[184:187], v[54:57]
	v_mfma_f32_16x16x32_bf16 v[38:41], v[148:151], v[192:195], v[38:41]
	v_mfma_f32_16x16x32_bf16 v[22:25], v[148:151], v[206:209], v[22:25]
	v_mfma_f32_16x16x32_bf16 v[6:9], v[148:151], v[214:217], v[6:9]
	v_mfma_f32_16x16x32_bf16 v[50:53], v[156:159], v[184:187], v[50:53]
	v_mfma_f32_16x16x32_bf16 v[34:37], v[156:159], v[192:195], v[34:37]
	v_mfma_f32_16x16x32_bf16 v[18:21], v[156:159], v[206:209], v[18:21]
	v_mfma_f32_16x16x32_bf16 v[2:5], v[156:159], v[214:217], v[2:5]
	s_setprio 0
	s_setprio 1
	v_mfma_f32_16x16x32_bf16 v[62:65], v[160:163], v[180:183], v[62:65]
	v_mfma_f32_16x16x32_bf16 v[46:49], v[160:163], v[188:191], v[46:49]
	v_mfma_f32_16x16x32_bf16 v[30:33], v[160:163], v[202:205], v[30:33]
	v_mfma_f32_16x16x32_bf16 v[10:13], v[160:163], v[210:213], v[10:13]
	v_mfma_f32_16x16x32_bf16 v[58:61], v[168:171], v[180:183], v[58:61]
	v_mfma_f32_16x16x32_bf16 v[42:45], v[168:171], v[188:191], v[42:45]
	v_mfma_f32_16x16x32_bf16 v[26:29], v[168:171], v[202:205], v[26:29]
	v_mfma_f32_16x16x32_bf16 v[14:17], v[168:171], v[210:213], v[14:17]
	v_mfma_f32_16x16x32_bf16 v[62:65], v[164:167], v[184:187], v[62:65]
	v_mfma_f32_16x16x32_bf16 v[46:49], v[164:167], v[192:195], v[46:49]
	v_mfma_f32_16x16x32_bf16 v[30:33], v[164:167], v[206:209], v[30:33]
	v_mfma_f32_16x16x32_bf16 v[10:13], v[164:167], v[214:217], v[10:13]
	v_mfma_f32_16x16x32_bf16 v[58:61], v[172:175], v[184:187], v[58:61]
	v_mfma_f32_16x16x32_bf16 v[42:45], v[172:175], v[192:195], v[42:45]
	v_mfma_f32_16x16x32_bf16 v[26:29], v[172:175], v[206:209], v[26:29]
	v_mfma_f32_16x16x32_bf16 v[14:17], v[172:175], v[214:217], v[14:17]
	s_setprio 0
	s_barrier
	s_add_i32 s18, 0, 0x18000
	v_add_u32_e32 v0, s18, v176
	s_add_i32 vcc_lo, 0, 0x1c000
	ds_read_b128 v[144:147], v0
	ds_read_b128 v[148:151], v0 offset:1024
	ds_read_b128 v[152:155], v0 offset:2048
	ds_read_b128 v[156:159], v0 offset:3072
	v_add_u32_e32 v0, vcc_lo, v176
	ds_read_b128 v[160:163], v0
	ds_read_b128 v[164:167], v0 offset:1024
	ds_read_b128 v[168:171], v0 offset:2048
	ds_read_b128 v[172:175], v0 offset:3072
	s_add_u32 s38, s80, 0x40000
	s_addc_u32 s39, s81, 0
	s_mov_b32 m0, s94
	v_lshl_add_u64 v[226:227], s[38:39], 0, v[136:137]
	ds_read_b128 v[180:183], v178 offset:32768
	ds_read_b128 v[184:187], v178 offset:33792
	ds_read_b128 v[188:191], v178 offset:34816
	ds_read_b128 v[192:195], v178 offset:35840
	ds_read_b128 v[202:205], v178 offset:36864
	ds_read_b128 v[206:209], v178 offset:37888
	ds_read_b128 v[210:213], v178 offset:38912
	ds_read_b128 v[214:217], v178 offset:39936
	global_load_lds_dwordx4 v[226:227], off
	v_lshl_add_u64 v[226:227], s[38:39], 0, v[132:133]
	s_mov_b32 m0, s95
	s_nop 0
	global_load_lds_dwordx4 v[226:227], off
	s_waitcnt vmcnt(8)
	s_waitcnt lgkmcnt(0)
	s_barrier
	s_setprio 1
	s_waitcnt lgkmcnt(0)
	v_mfma_f32_16x16x32_bf16 v[118:121], v[144:147], v[180:183], v[118:121]
	v_mfma_f32_16x16x32_bf16 v[102:105], v[144:147], v[188:191], v[102:105]
	v_mfma_f32_16x16x32_bf16 v[86:89], v[144:147], v[202:205], v[86:89]
	v_mfma_f32_16x16x32_bf16 v[70:73], v[144:147], v[210:213], v[70:73]
	v_mfma_f32_16x16x32_bf16 v[114:117], v[152:155], v[180:183], v[114:117]
	v_mfma_f32_16x16x32_bf16 v[98:101], v[152:155], v[188:191], v[98:101]
	v_mfma_f32_16x16x32_bf16 v[82:85], v[152:155], v[202:205], v[82:85]
	v_mfma_f32_16x16x32_bf16 v[66:69], v[152:155], v[210:213], v[66:69]
	v_mfma_f32_16x16x32_bf16 v[118:121], v[148:151], v[184:187], v[118:121]
	v_mfma_f32_16x16x32_bf16 v[102:105], v[148:151], v[192:195], v[102:105]
	v_mfma_f32_16x16x32_bf16 v[86:89], v[148:151], v[206:209], v[86:89]
	v_mfma_f32_16x16x32_bf16 v[70:73], v[148:151], v[214:217], v[70:73]
	v_mfma_f32_16x16x32_bf16 v[114:117], v[156:159], v[184:187], v[114:117]
	v_mfma_f32_16x16x32_bf16 v[98:101], v[156:159], v[192:195], v[98:101]
	v_mfma_f32_16x16x32_bf16 v[82:85], v[156:159], v[206:209], v[82:85]
	v_mfma_f32_16x16x32_bf16 v[66:69], v[156:159], v[214:217], v[66:69]
	s_setprio 0
	s_setprio 1
	v_mfma_f32_16x16x32_bf16 v[126:129], v[160:163], v[180:183], v[126:129]
	v_mfma_f32_16x16x32_bf16 v[110:113], v[160:163], v[188:191], v[110:113]
	v_mfma_f32_16x16x32_bf16 v[94:97], v[160:163], v[202:205], v[94:97]
	v_mfma_f32_16x16x32_bf16 v[78:81], v[160:163], v[210:213], v[78:81]
	v_mfma_f32_16x16x32_bf16 v[122:125], v[168:171], v[180:183], v[122:125]
	v_mfma_f32_16x16x32_bf16 v[106:109], v[168:171], v[188:191], v[106:109]
	v_mfma_f32_16x16x32_bf16 v[90:93], v[168:171], v[202:205], v[90:93]
	v_mfma_f32_16x16x32_bf16 v[74:77], v[168:171], v[210:213], v[74:77]
	v_mfma_f32_16x16x32_bf16 v[126:129], v[164:167], v[184:187], v[126:129]
	v_mfma_f32_16x16x32_bf16 v[110:113], v[164:167], v[192:195], v[110:113]
	v_mfma_f32_16x16x32_bf16 v[94:97], v[164:167], v[206:209], v[94:97]
	v_mfma_f32_16x16x32_bf16 v[78:81], v[164:167], v[214:217], v[78:81]
	v_mfma_f32_16x16x32_bf16 v[122:125], v[172:175], v[184:187], v[122:125]
	v_mfma_f32_16x16x32_bf16 v[106:109], v[172:175], v[192:195], v[106:109]
	v_mfma_f32_16x16x32_bf16 v[90:93], v[172:175], v[206:209], v[90:93]
	v_mfma_f32_16x16x32_bf16 v[74:77], v[172:175], v[214:217], v[74:77]
	s_setprio 0
	s_barrier
; #define PG8_STAGE(bufoff, gbase, voff) do { _Pragma("unroll") for (int _i = 0; _i < 2; ++_i) \
;         __builtin_amdgcn_global_load_lds((const unsigned*)((const char*)(gbase) + (voff)[_i]), (PG8_LAS unsigned*)(lds + (bufoff) + ldsw + _i * 8192), 16, 0, 0); } while (0)
; #define PG8_LDA(dst, b, h) do { _Pragma("unroll") for (int m = 0; m < 4; ++m) _Pragma("unroll") for (int k = 0; k < 2; ++k) dst[m][k] = *(const PG8_LAS bf16x8*)(lds + PG8_SA(b, h) + aoff + m * 2048 + k * 1024); } while (0)
; #define PG8_MMA(ai, bj, At, Bt) do { __builtin_amdgcn_s_setprio(1); _Pragma("unroll") for (int m = 0; m < 4; ++m) _Pragma("unroll") for (int n = 0; n < 2; ++n) _Pragma("unroll") for (int k = 0; k < 2; ++k) \
;         acc[ai][bj][m][n] = __builtin_amdgcn_mfma_f32_16x16x32_bf16(Bt[n][k], At[m][k], acc[ai][bj][m][n], 0, 0, 0); __builtin_amdgcn_s_setprio(0); } while (0)
; #define PG8_WAIT_V(n) asm volatile("s_waitcnt vmcnt(" #n ")" ::: "memory")
; #define PG8_WAIT_L(n) asm volatile("s_waitcnt lgkmcnt(" #n ")" ::: "memory")
; #define PG8_BAR __builtin_amdgcn_s_barrier()
; #define PG8_SCHED __builtin_amdgcn_sched_barrier(0)
; template <class Epi, class Sched, bool ALIGN_EPI = false, bool SP2 = false>
; __device__ __forceinline__ void gemm_phase(PG8_LAS unsigned char* lds, const Gemm g, const Sched& S, const Epi& E) {
;     ...
;         for (int t = 0; t < nt; t += 2) {
;             const bool last = (t == nt - 2);
;             const char* a1 = cA + (size_t)(t + 1) * kstep;
;             const char* a2 = last ? nA : cA + (size_t)(t + 2) * kstep; const char* b2 = last ? nB : cB + (size_t)(t + 2) * kstep;
;             const char* a3 = a2 + kstep; const char* b3 = b2 + kstep;
;             if (last && has_next) S.a_ready(nxt);
;     ...
;             PG8_LDA(At, 1, 1); PG8_STAGE(PG8_SB(1, 0), b3, voffB); PG8_STAGE(PG8_SB(1, 1), b3 + hstep, voffB); PG8_STAGE(PG8_SA(1, 0), a3, voffA);
;             PG8_WAIT_V(8); PG8_WAIT_L(0); PG8_BAR; PG8_MMA(1, 0, At, B0); PG8_MMA(1, 1, At, B1); PG8_BAR; PG8_SCHED;
	s_add_i32 s18, s18, s91
	v_lshl_add_u64 v[218:219], v[218:219], 0, s[30:31]
	s_mov_b32 m0, s18
	ds_read_b128 v[180:183], v178 offset:49152
	ds_read_b128 v[184:187], v178 offset:50176
	ds_read_b128 v[188:191], v178 offset:51200
	ds_read_b128 v[192:195], v178 offset:52224
	ds_read_b128 v[202:205], v178 offset:53248
	ds_read_b128 v[206:209], v178 offset:54272
	ds_read_b128 v[210:213], v178 offset:55296
	ds_read_b128 v[214:217], v178 offset:56320
	global_load_lds_dwordx4 v[218:219], off
	s_add_i32 m0, s18, 0x2000
	s_add_u32 s38, s44, 0x40080
	v_lshl_add_u64 v[218:219], v[220:221], 0, s[30:31]
	s_addc_u32 s39, s45, 0
	s_add_i32 s18, vcc_lo, s91
	global_load_lds_dwordx4 v[218:219], off
	v_lshl_add_u64 v[218:219], s[38:39], 0, v[134:135]
	s_mov_b32 m0, s18
	s_nop 0
	global_load_lds_dwordx4 v[218:219], off
	v_lshl_add_u64 v[218:219], s[38:39], 0, v[130:131]
	s_add_i32 m0, s18, 0x2000
	s_nop 0
	global_load_lds_dwordx4 v[218:219], off
	v_lshl_add_u64 v[218:219], v[222:223], 0, s[30:31]
	s_mov_b32 m0, s7
	s_nop 0
	global_load_lds_dwordx4 v[218:219], off
	v_lshl_add_u64 v[218:219], v[224:225], 0, s[30:31]
	s_mov_b32 m0, s96
	s_nop 0
	global_load_lds_dwordx4 v[218:219], off
	s_waitcnt vmcnt(8)
	s_waitcnt lgkmcnt(0)
	s_barrier
	s_setprio 1
	s_waitcnt lgkmcnt(0)
	v_mfma_f32_16x16x32_bf16 v[54:57], v[144:147], v[180:183], v[54:57]
	v_mfma_f32_16x16x32_bf16 v[38:41], v[144:147], v[188:191], v[38:41]
	v_mfma_f32_16x16x32_bf16 v[22:25], v[144:147], v[202:205], v[22:25]
	v_mfma_f32_16x16x32_bf16 v[6:9], v[144:147], v[210:213], v[6:9]
	v_mfma_f32_16x16x32_bf16 v[50:53], v[152:155], v[180:183], v[50:53]
	v_mfma_f32_16x16x32_bf16 v[34:37], v[152:155], v[188:191], v[34:37]
	v_mfma_f32_16x16x32_bf16 v[18:21], v[152:155], v[202:205], v[18:21]
	v_mfma_f32_16x16x32_bf16 v[2:5], v[152:155], v[210:213], v[2:5]
	v_mfma_f32_16x16x32_bf16 v[54:57], v[148:151], v[184:187], v[54:57]
	v_mfma_f32_16x16x32_bf16 v[38:41], v[148:151], v[192:195], v[38:41]
	v_mfma_f32_16x16x32_bf16 v[22:25], v[148:151], v[206:209], v[22:25]
	v_mfma_f32_16x16x32_bf16 v[6:9], v[148:151], v[214:217], v[6:9]
	v_mfma_f32_16x16x32_bf16 v[50:53], v[156:159], v[184:187], v[50:53]
	v_mfma_f32_16x16x32_bf16 v[34:37], v[156:159], v[192:195], v[34:37]
	v_mfma_f32_16x16x32_bf16 v[18:21], v[156:159], v[206:209], v[18:21]
	v_mfma_f32_16x16x32_bf16 v[2:5], v[156:159], v[214:217], v[2:5]
	s_setprio 0
	s_setprio 1
	v_mfma_f32_16x16x32_bf16 v[62:65], v[160:163], v[180:183], v[62:65]
	v_mfma_f32_16x16x32_bf16 v[46:49], v[160:163], v[188:191], v[46:49]
	v_mfma_f32_16x16x32_bf16 v[30:33], v[160:163], v[202:205], v[30:33]
	v_mfma_f32_16x16x32_bf16 v[10:13], v[160:163], v[210:213], v[10:13]
	v_mfma_f32_16x16x32_bf16 v[58:61], v[168:171], v[180:183], v[58:61]
	v_mfma_f32_16x16x32_bf16 v[42:45], v[168:171], v[188:191], v[42:45]
	v_mfma_f32_16x16x32_bf16 v[26:29], v[168:171], v[202:205], v[26:29]
	v_mfma_f32_16x16x32_bf16 v[14:17], v[168:171], v[210:213], v[14:17]
	v_mfma_f32_16x16x32_bf16 v[62:65], v[164:167], v[184:187], v[62:65]
	v_mfma_f32_16x16x32_bf16 v[46:49], v[164:167], v[192:195], v[46:49]
	v_mfma_f32_16x16x32_bf16 v[30:33], v[164:167], v[206:209], v[30:33]
	v_mfma_f32_16x16x32_bf16 v[10:13], v[164:167], v[214:217], v[10:13]
	v_mfma_f32_16x16x32_bf16 v[58:61], v[172:175], v[184:187], v[58:61]
	v_mfma_f32_16x16x32_bf16 v[42:45], v[172:175], v[192:195], v[42:45]
	v_mfma_f32_16x16x32_bf16 v[26:29], v[172:175], v[206:209], v[26:29]
	v_mfma_f32_16x16x32_bf16 v[14:17], v[172:175], v[214:217], v[14:17]
	s_setprio 0
	s_barrier
	s_add_i32 s85, s85, 2
	s_add_u32 s46, s46, 0x100
	s_addc_u32 s47, s47, 0
	s_add_u32 s83, s83, 0x100
	s_addc_u32 s84, s84, 0
	s_cmp_gt_u32 s85, 13
	s_cbranch_scc0 .LBB0_132
	s_and_b64 vcc, exec, s[10:11]
	s_cbranch_vccz .LBB0_135
	s_barrier

; #define PG8_STAGE(bufoff, gbase, voff) do { _Pragma("unroll") for (int _i = 0; _i < 2; ++_i) \
;         __builtin_amdgcn_global_load_lds((const unsigned*)((const char*)(gbase) + (voff)[_i]), (PG8_LAS unsigned*)(lds + (bufoff) + ldsw + _i * 8192), 16, 0, 0); } while (0)
; #define PG8_LDA(dst, b, h) do { _Pragma("unroll") for (int m = 0; m < 4; ++m) _Pragma("unroll") for (int k = 0; k < 2; ++k) dst[m][k] = *(const PG8_LAS bf16x8*)(lds + PG8_SA(b, h) + aoff + m * 2048 + k * 1024); } while (0)
; #define PG8_LDB(dst, b, h) do { _Pragma("unroll") for (int n = 0; n < 2; ++n) _Pragma("unroll") for (int k = 0; k < 2; ++k) dst[n][k] = *(const PG8_LAS bf16x8*)(lds + PG8_SB(b, h) + boff + n * 2048 + k * 1024); } while (0)
; #define PG8_MMA(ai, bj, At, Bt) do { __builtin_amdgcn_s_setprio(1); _Pragma("unroll") for (int m = 0; m < 4; ++m) _Pragma("unroll") for (int n = 0; n < 2; ++n) _Pragma("unroll") for (int k = 0; k < 2; ++k) \
;         acc[ai][bj][m][n] = __builtin_amdgcn_mfma_f32_16x16x32_bf16(Bt[n][k], At[m][k], acc[ai][bj][m][n], 0, 0, 0); __builtin_amdgcn_s_setprio(0); } while (0)
; #define PG8_WAIT_V(n) asm volatile("s_waitcnt vmcnt(" #n ")" ::: "memory")
; #define PG8_WAIT_L(n) asm volatile("s_waitcnt lgkmcnt(" #n ")" ::: "memory")
; template <class Epi, class Sched, bool ALIGN_EPI = false, bool SP2 = false>
; __device__ __forceinline__ void gemm_phase(PG8_LAS unsigned char* lds, const Gemm g, const Sched& S, const Epi& E) {
;     ...
;             const bool last = (t == nt - 2);
;             const char* a1 = cA + (size_t)(t + 1) * kstep;
;             const char* a2 = last ? nA : cA + (size_t)(t + 2) * kstep; const char* b2 = last ? nB : cB + (size_t)(t + 2) * kstep;
;             const char* a3 = a2 + kstep; const char* b3 = b2 + kstep;
;             if (last && has_next) S.a_ready(nxt);
;             if constexpr (SP2) {
;             PG8_LDB(B0, 0, 0); PG8_LDB(B1, 0, 1); PG8_SCHED; PG8_LDA(At, 0, 0); PG8_STAGE(PG8_SA(1, 1), a1 + hstep, voffA);
;             PG8_WAIT_V(8); PG8_WAIT_L(0); PG8_BAR; PG8_MMA(0, 0, At, B0); PG8_MMA(0, 1, At, B1); PG8_BAR; PG8_SCHED;
;             PG8_LDA(At, 0, 1); PG8_STAGE(PG8_SB(0, 0), b2, voffB); PG8_STAGE(PG8_SB(0, 1), b2 + hstep, voffB); PG8_STAGE(PG8_SA(0, 0), a2, voffA);
;             PG8_WAIT_V(8); PG8_WAIT_L(0); PG8_BAR; PG8_MMA(1, 0, At, B0); PG8_MMA(1, 1, At, B1); PG8_BAR; PG8_SCHED;
.LBB0_220:
	s_add_u32 s18, s60, 0xfffc0080
	s_addc_u32 s38, s61, -1
	s_add_i32 s39, 0, 0x10000
	s_cmp_eq_u32 s82, 12
	s_cselect_b32 s65, s47, s38
	s_cselect_b32 s64, s78, s18
	v_add_u32_e32 v145, s39, v141
	s_cselect_b32 s57, s49, s81
	s_cselect_b32 s56, s79, s80
	s_add_i32 s18, 0, 0x14000
	ds_read_b128 v[146:149], v145
	ds_read_b128 v[150:153], v145 offset:1024
	ds_read_b128 v[154:157], v145 offset:2048
	ds_read_b128 v[158:161], v145 offset:3072
	v_add_u32_e32 v145, s18, v141
	ds_read_b128 v[162:165], v145
	ds_read_b128 v[166:169], v145 offset:1024
	ds_read_b128 v[170:173], v145 offset:2048
	ds_read_b128 v[174:177], v145 offset:3072
	v_lshl_add_u64 v[194:195], s[60:61], 0, v[136:137]
	s_add_i32 m0, s29, 0xc000
	ds_read_b128 v[178:181], v144
	ds_read_b128 v[182:185], v144 offset:1024
	ds_read_b128 v[186:189], v144 offset:2048
	ds_read_b128 v[190:193], v144 offset:3072
	ds_read_b128 v[202:205], v144 offset:4096
	ds_read_b128 v[206:209], v144 offset:5120
	ds_read_b128 v[210:213], v144 offset:6144
	ds_read_b128 v[214:217], v144 offset:7168
	global_load_lds_dwordx4 v[194:195], off
	v_lshl_add_u64 v[194:195], s[60:61], 0, v[138:139]
	s_add_i32 m0, s29, 0xe000
	s_nop 0
	global_load_lds_dwordx4 v[194:195], off
	s_waitcnt vmcnt(8)
	s_waitcnt lgkmcnt(0)
	s_barrier
	s_setprio 1
	s_waitcnt lgkmcnt(0)
	v_mfma_f32_16x16x32_bf16 v[114:117], v[146:149], v[178:181], v[114:117]
	v_mfma_f32_16x16x32_bf16 v[98:101], v[146:149], v[186:189], v[98:101]
	v_mfma_f32_16x16x32_bf16 v[82:85], v[146:149], v[202:205], v[82:85]
	v_mfma_f32_16x16x32_bf16 v[66:69], v[146:149], v[210:213], v[66:69]
	v_mfma_f32_16x16x32_bf16 v[118:121], v[154:157], v[178:181], v[118:121]
	v_mfma_f32_16x16x32_bf16 v[102:105], v[154:157], v[186:189], v[102:105]
	v_mfma_f32_16x16x32_bf16 v[86:89], v[154:157], v[202:205], v[86:89]
	v_mfma_f32_16x16x32_bf16 v[70:73], v[154:157], v[210:213], v[70:73]
	v_mfma_f32_16x16x32_bf16 v[114:117], v[150:153], v[182:185], v[114:117]
	v_mfma_f32_16x16x32_bf16 v[98:101], v[150:153], v[190:193], v[98:101]
	v_mfma_f32_16x16x32_bf16 v[82:85], v[150:153], v[206:209], v[82:85]
	v_mfma_f32_16x16x32_bf16 v[66:69], v[150:153], v[214:217], v[66:69]
	v_mfma_f32_16x16x32_bf16 v[118:121], v[158:161], v[182:185], v[118:121]
	v_mfma_f32_16x16x32_bf16 v[102:105], v[158:161], v[190:193], v[102:105]
	v_mfma_f32_16x16x32_bf16 v[86:89], v[158:161], v[206:209], v[86:89]
	v_mfma_f32_16x16x32_bf16 v[70:73], v[158:161], v[214:217], v[70:73]
	s_setprio 0
	s_setprio 1
	v_mfma_f32_16x16x32_bf16 v[122:125], v[162:165], v[178:181], v[122:125]
	v_mfma_f32_16x16x32_bf16 v[106:109], v[162:165], v[186:189], v[106:109]
	v_mfma_f32_16x16x32_bf16 v[90:93], v[162:165], v[202:205], v[90:93]
	v_mfma_f32_16x16x32_bf16 v[74:77], v[162:165], v[210:213], v[74:77]
	v_mfma_f32_16x16x32_bf16 v[126:129], v[170:173], v[178:181], v[126:129]
	v_mfma_f32_16x16x32_bf16 v[110:113], v[170:173], v[186:189], v[110:113]
	v_mfma_f32_16x16x32_bf16 v[94:97], v[170:173], v[202:205], v[94:97]
	v_mfma_f32_16x16x32_bf16 v[78:81], v[170:173], v[210:213], v[78:81]
	v_mfma_f32_16x16x32_bf16 v[122:125], v[166:169], v[182:185], v[122:125]
	v_mfma_f32_16x16x32_bf16 v[106:109], v[166:169], v[190:193], v[106:109]
	v_mfma_f32_16x16x32_bf16 v[90:93], v[166:169], v[206:209], v[90:93]
	v_mfma_f32_16x16x32_bf16 v[74:77], v[166:169], v[214:217], v[74:77]
	v_mfma_f32_16x16x32_bf16 v[126:129], v[174:177], v[182:185], v[126:129]
	v_mfma_f32_16x16x32_bf16 v[110:113], v[174:177], v[190:193], v[110:113]
	v_mfma_f32_16x16x32_bf16 v[94:97], v[174:177], v[206:209], v[94:97]
	v_mfma_f32_16x16x32_bf16 v[78:81], v[174:177], v[214:217], v[78:81]
	s_setprio 0
	s_barrier
	s_add_i32 s38, s39, s27
	v_lshl_add_u64 v[194:195], s[56:57], 0, v[0:1]
	s_mov_b32 m0, s38
	ds_read_b128 v[178:181], v144 offset:16384
	ds_read_b128 v[182:185], v144 offset:17408
	ds_read_b128 v[186:189], v144 offset:18432
	ds_read_b128 v[190:193], v144 offset:19456
	ds_read_b128 v[202:205], v144 offset:20480
	ds_read_b128 v[206:209], v144 offset:21504
	ds_read_b128 v[210:213], v144 offset:22528
	ds_read_b128 v[214:217], v144 offset:23552
	global_load_lds_dwordx4 v[194:195], off
	s_add_i32 m0, s38, 0x2000
	s_add_u32 s38, s56, 0x40000
	v_lshl_add_u64 v[218:219], s[56:57], 0, v[130:131]
	s_addc_u32 s39, s57, 0
	s_add_i32 s18, s18, s27
	global_load_lds_dwordx4 v[218:219], off
	v_lshl_add_u64 v[220:221], s[38:39], 0, v[0:1]
	s_mov_b32 m0, s18
	v_lshl_add_u64 v[222:223], s[64:65], 0, v[132:133]
	global_load_lds_dwordx4 v[220:221], off
	v_lshl_add_u64 v[220:221], s[38:39], 0, v[130:131]
	s_add_i32 m0, s18, 0x2000
	s_nop 0
	global_load_lds_dwordx4 v[220:221], off
	v_lshl_add_u64 v[220:221], s[64:65], 0, v[134:135]
	s_mov_b32 m0, s29
	s_nop 0
	global_load_lds_dwordx4 v[220:221], off
	s_mov_b32 m0, s33
	s_nop 0
	global_load_lds_dwordx4 v[222:223], off
	s_waitcnt vmcnt(8)
	s_waitcnt lgkmcnt(0)
	s_barrier
; #define PG8_STAGE(bufoff, gbase, voff) do { _Pragma("unroll") for (int _i = 0; _i < 2; ++_i) \
;         __builtin_amdgcn_global_load_lds((const unsigned*)((const char*)(gbase) + (voff)[_i]), (PG8_LAS unsigned*)(lds + (bufoff) + ldsw + _i * 8192), 16, 0, 0); } while (0)
; #define PG8_LDA(dst, b, h) do { _Pragma("unroll") for (int m = 0; m < 4; ++m) _Pragma("unroll") for (int k = 0; k < 2; ++k) dst[m][k] = *(const PG8_LAS bf16x8*)(lds + PG8_SA(b, h) + aoff + m * 2048 + k * 1024); } while (0)
; #define PG8_LDB(dst, b, h) do { _Pragma("unroll") for (int n = 0; n < 2; ++n) _Pragma("unroll") for (int k = 0; k < 2; ++k) dst[n][k] = *(const PG8_LAS bf16x8*)(lds + PG8_SB(b, h) + boff + n * 2048 + k * 1024); } while (0)
; #define PG8_MMA(ai, bj, At, Bt) do { __builtin_amdgcn_s_setprio(1); _Pragma("unroll") for (int m = 0; m < 4; ++m) _Pragma("unroll") for (int n = 0; n < 2; ++n) _Pragma("unroll") for (int k = 0; k < 2; ++k) \
;         acc[ai][bj][m][n] = __builtin_amdgcn_mfma_f32_16x16x32_bf16(Bt[n][k], At[m][k], acc[ai][bj][m][n], 0, 0, 0); __builtin_amdgcn_s_setprio(0); } while (0)
; #define PG8_WAIT_V(n) asm volatile("s_waitcnt vmcnt(" #n ")" ::: "memory")
; #define PG8_WAIT_L(n) asm volatile("s_waitcnt lgkmcnt(" #n ")" ::: "memory")
; #define PG8_BAR __builtin_amdgcn_s_barrier()
; #define PG8_SCHED __builtin_amdgcn_sched_barrier(0)
; template <class Epi, class Sched, bool ALIGN_EPI = false, bool SP2 = false>
; __device__ __forceinline__ void gemm_phase(PG8_LAS unsigned char* lds, const Gemm g, const Sched& S, const Epi& E) {
;     ...
;             PG8_WAIT_V(8); PG8_WAIT_L(0); PG8_BAR; PG8_MMA(1, 0, At, B0); PG8_MMA(1, 1, At, B1); PG8_BAR; PG8_SCHED;
;             PG8_LDB(B0, 1, 0); PG8_LDB(B1, 1, 1); PG8_SCHED; PG8_LDA(At, 1, 0); PG8_STAGE(PG8_SA(0, 1), a2 + hstep, voffA);
;             PG8_WAIT_V(8); PG8_WAIT_L(0); PG8_BAR; PG8_MMA(0, 0, At, B0); PG8_MMA(0, 1, At, B1); PG8_BAR; PG8_SCHED;
	s_setprio 1
	s_waitcnt lgkmcnt(0)
	v_mfma_f32_16x16x32_bf16 v[50:53], v[146:149], v[178:181], v[50:53]
	v_mfma_f32_16x16x32_bf16 v[34:37], v[146:149], v[186:189], v[34:37]
	v_mfma_f32_16x16x32_bf16 v[18:21], v[146:149], v[202:205], v[18:21]
	v_mfma_f32_16x16x32_bf16 v[2:5], v[146:149], v[210:213], v[2:5]
	v_mfma_f32_16x16x32_bf16 v[54:57], v[154:157], v[178:181], v[54:57]
	v_mfma_f32_16x16x32_bf16 v[38:41], v[154:157], v[186:189], v[38:41]
	v_mfma_f32_16x16x32_bf16 v[22:25], v[154:157], v[202:205], v[22:25]
	v_mfma_f32_16x16x32_bf16 v[6:9], v[154:157], v[210:213], v[6:9]
	v_mfma_f32_16x16x32_bf16 v[50:53], v[150:153], v[182:185], v[50:53]
	v_mfma_f32_16x16x32_bf16 v[34:37], v[150:153], v[190:193], v[34:37]
	v_mfma_f32_16x16x32_bf16 v[18:21], v[150:153], v[206:209], v[18:21]
	v_mfma_f32_16x16x32_bf16 v[2:5], v[150:153], v[214:217], v[2:5]
	v_mfma_f32_16x16x32_bf16 v[54:57], v[158:161], v[182:185], v[54:57]
	v_mfma_f32_16x16x32_bf16 v[38:41], v[158:161], v[190:193], v[38:41]
	v_mfma_f32_16x16x32_bf16 v[22:25], v[158:161], v[206:209], v[22:25]
	v_mfma_f32_16x16x32_bf16 v[6:9], v[158:161], v[214:217], v[6:9]
	s_setprio 0
	s_setprio 1
	v_mfma_f32_16x16x32_bf16 v[58:61], v[162:165], v[178:181], v[58:61]
	v_mfma_f32_16x16x32_bf16 v[42:45], v[162:165], v[186:189], v[42:45]
	v_mfma_f32_16x16x32_bf16 v[26:29], v[162:165], v[202:205], v[26:29]
	v_mfma_f32_16x16x32_bf16 v[10:13], v[162:165], v[210:213], v[10:13]
	v_mfma_f32_16x16x32_bf16 v[62:65], v[170:173], v[178:181], v[62:65]
	v_mfma_f32_16x16x32_bf16 v[46:49], v[170:173], v[186:189], v[46:49]
	v_mfma_f32_16x16x32_bf16 v[30:33], v[170:173], v[202:205], v[30:33]
	v_mfma_f32_16x16x32_bf16 v[14:17], v[170:173], v[210:213], v[14:17]
	v_mfma_f32_16x16x32_bf16 v[58:61], v[166:169], v[182:185], v[58:61]
	v_mfma_f32_16x16x32_bf16 v[42:45], v[166:169], v[190:193], v[42:45]
	v_mfma_f32_16x16x32_bf16 v[26:29], v[166:169], v[206:209], v[26:29]
	v_mfma_f32_16x16x32_bf16 v[10:13], v[166:169], v[214:217], v[10:13]
	v_mfma_f32_16x16x32_bf16 v[62:65], v[174:177], v[182:185], v[62:65]
	v_mfma_f32_16x16x32_bf16 v[46:49], v[174:177], v[190:193], v[46:49]
	v_mfma_f32_16x16x32_bf16 v[30:33], v[174:177], v[206:209], v[30:33]
	v_mfma_f32_16x16x32_bf16 v[14:17], v[174:177], v[214:217], v[14:17]
	s_setprio 0
	s_barrier
	s_add_i32 s18, 0, 0x18000
	v_add_u32_e32 v145, s18, v141
	s_add_i32 s83, 0, 0x1c000
	ds_read_b128 v[146:149], v145
	ds_read_b128 v[150:153], v145 offset:1024
	ds_read_b128 v[154:157], v145 offset:2048
	ds_read_b128 v[158:161], v145 offset:3072
	v_add_u32_e32 v145, s83, v141
	ds_read_b128 v[162:165], v145
	ds_read_b128 v[166:169], v145 offset:1024
	ds_read_b128 v[170:173], v145 offset:2048
	ds_read_b128 v[174:177], v145 offset:3072
	s_add_u32 s38, s64, 0x40000
	s_addc_u32 s39, s65, 0
	s_mov_b32 m0, s58
	v_lshl_add_u64 v[224:225], s[38:39], 0, v[134:135]
	ds_read_b128 v[178:181], v144 offset:32768
	ds_read_b128 v[182:185], v144 offset:33792
	ds_read_b128 v[186:189], v144 offset:34816
	ds_read_b128 v[190:193], v144 offset:35840
	ds_read_b128 v[202:205], v144 offset:36864
	ds_read_b128 v[206:209], v144 offset:37888
	ds_read_b128 v[210:213], v144 offset:38912
	ds_read_b128 v[214:217], v144 offset:39936
	global_load_lds_dwordx4 v[224:225], off
	v_lshl_add_u64 v[224:225], s[38:39], 0, v[132:133]
	s_mov_b32 m0, s69
	s_nop 0
	global_load_lds_dwordx4 v[224:225], off
	s_waitcnt vmcnt(8)
	s_waitcnt lgkmcnt(0)
	s_barrier
	s_setprio 1
	s_waitcnt lgkmcnt(0)
	v_mfma_f32_16x16x32_bf16 v[114:117], v[146:149], v[178:181], v[114:117]
	v_mfma_f32_16x16x32_bf16 v[98:101], v[146:149], v[186:189], v[98:101]
	v_mfma_f32_16x16x32_bf16 v[82:85], v[146:149], v[202:205], v[82:85]
	v_mfma_f32_16x16x32_bf16 v[66:69], v[146:149], v[210:213], v[66:69]
	v_mfma_f32_16x16x32_bf16 v[118:121], v[154:157], v[178:181], v[118:121]
	v_mfma_f32_16x16x32_bf16 v[102:105], v[154:157], v[186:189], v[102:105]
	v_mfma_f32_16x16x32_bf16 v[86:89], v[154:157], v[202:205], v[86:89]
	v_mfma_f32_16x16x32_bf16 v[70:73], v[154:157], v[210:213], v[70:73]
	v_mfma_f32_16x16x32_bf16 v[114:117], v[150:153], v[182:185], v[114:117]
	v_mfma_f32_16x16x32_bf16 v[98:101], v[150:153], v[190:193], v[98:101]
	v_mfma_f32_16x16x32_bf16 v[82:85], v[150:153], v[206:209], v[82:85]
	v_mfma_f32_16x16x32_bf16 v[66:69], v[150:153], v[214:217], v[66:69]
	v_mfma_f32_16x16x32_bf16 v[118:121], v[158:161], v[182:185], v[118:121]
	v_mfma_f32_16x16x32_bf16 v[102:105], v[158:161], v[190:193], v[102:105]
	v_mfma_f32_16x16x32_bf16 v[86:89], v[158:161], v[206:209], v[86:89]
	v_mfma_f32_16x16x32_bf16 v[70:73], v[158:161], v[214:217], v[70:73]
	s_setprio 0
	s_setprio 1
	v_mfma_f32_16x16x32_bf16 v[122:125], v[162:165], v[178:181], v[122:125]
	v_mfma_f32_16x16x32_bf16 v[106:109], v[162:165], v[186:189], v[106:109]
	v_mfma_f32_16x16x32_bf16 v[90:93], v[162:165], v[202:205], v[90:93]
	v_mfma_f32_16x16x32_bf16 v[74:77], v[162:165], v[210:213], v[74:77]
	v_mfma_f32_16x16x32_bf16 v[126:129], v[170:173], v[178:181], v[126:129]
	v_mfma_f32_16x16x32_bf16 v[110:113], v[170:173], v[186:189], v[110:113]
	v_mfma_f32_16x16x32_bf16 v[94:97], v[170:173], v[202:205], v[94:97]
	v_mfma_f32_16x16x32_bf16 v[78:81], v[170:173], v[210:213], v[78:81]
	v_mfma_f32_16x16x32_bf16 v[122:125], v[166:169], v[182:185], v[122:125]
	v_mfma_f32_16x16x32_bf16 v[106:109], v[166:169], v[190:193], v[106:109]
	v_mfma_f32_16x16x32_bf16 v[90:93], v[166:169], v[206:209], v[90:93]
	v_mfma_f32_16x16x32_bf16 v[74:77], v[166:169], v[214:217], v[74:77]
	v_mfma_f32_16x16x32_bf16 v[126:129], v[174:177], v[182:185], v[126:129]
	v_mfma_f32_16x16x32_bf16 v[110:113], v[174:177], v[190:193], v[110:113]
	v_mfma_f32_16x16x32_bf16 v[94:97], v[174:177], v[206:209], v[94:97]
	v_mfma_f32_16x16x32_bf16 v[78:81], v[174:177], v[214:217], v[78:81]
	s_setprio 0
	s_barrier
; #define PG8_STAGE(bufoff, gbase, voff) do { _Pragma("unroll") for (int _i = 0; _i < 2; ++_i) \
;         __builtin_amdgcn_global_load_lds((const unsigned*)((const char*)(gbase) + (voff)[_i]), (PG8_LAS unsigned*)(lds + (bufoff) + ldsw + _i * 8192), 16, 0, 0); } while (0)
; #define PG8_LDA(dst, b, h) do { _Pragma("unroll") for (int m = 0; m < 4; ++m) _Pragma("unroll") for (int k = 0; k < 2; ++k) dst[m][k] = *(const PG8_LAS bf16x8*)(lds + PG8_SA(b, h) + aoff + m * 2048 + k * 1024); } while (0)
; #define PG8_MMA(ai, bj, At, Bt) do { __builtin_amdgcn_s_setprio(1); _Pragma("unroll") for (int m = 0; m < 4; ++m) _Pragma("unroll") for (int n = 0; n < 2; ++n) _Pragma("unroll") for (int k = 0; k < 2; ++k) \
;         acc[ai][bj][m][n] = __builtin_amdgcn_mfma_f32_16x16x32_bf16(Bt[n][k], At[m][k], acc[ai][bj][m][n], 0, 0, 0); __builtin_amdgcn_s_setprio(0); } while (0)
; #define PG8_WAIT_V(n) asm volatile("s_waitcnt vmcnt(" #n ")" ::: "memory")
; #define PG8_WAIT_L(n) asm volatile("s_waitcnt lgkmcnt(" #n ")" ::: "memory")
; #define PG8_BAR __builtin_amdgcn_s_barrier()
; #define PG8_SCHED __builtin_amdgcn_sched_barrier(0)
; template <class Epi, class Sched, bool ALIGN_EPI = false, bool SP2 = false>
; __device__ __forceinline__ void gemm_phase(PG8_LAS unsigned char* lds, const Gemm g, const Sched& S, const Epi& E) {
;     ...
;         for (int t = 0; t < nt; t += 2) {
;             const bool last = (t == nt - 2);
;             const char* a1 = cA + (size_t)(t + 1) * kstep;
;             const char* a2 = last ? nA : cA + (size_t)(t + 2) * kstep; const char* b2 = last ? nB : cB + (size_t)(t + 2) * kstep;
;             const char* a3 = a2 + kstep; const char* b3 = b2 + kstep;
;             if (last && has_next) S.a_ready(nxt);
;     ...
;             PG8_LDA(At, 1, 1); PG8_STAGE(PG8_SB(1, 0), b3, voffB); PG8_STAGE(PG8_SB(1, 1), b3 + hstep, voffB); PG8_STAGE(PG8_SA(1, 0), a3, voffA);
;             PG8_WAIT_V(8); PG8_WAIT_L(0); PG8_BAR; PG8_MMA(1, 0, At, B0); PG8_MMA(1, 1, At, B1); PG8_BAR; PG8_SCHED;
	s_add_i32 s18, s18, s27
	v_lshl_add_u64 v[194:195], v[194:195], 0, s[30:31]
	s_mov_b32 m0, s18
	ds_read_b128 v[178:181], v144 offset:49152
	ds_read_b128 v[182:185], v144 offset:50176
	ds_read_b128 v[186:189], v144 offset:51200
	ds_read_b128 v[190:193], v144 offset:52224
	ds_read_b128 v[202:205], v144 offset:53248
	ds_read_b128 v[206:209], v144 offset:54272
	ds_read_b128 v[210:213], v144 offset:55296
	ds_read_b128 v[214:217], v144 offset:56320
	global_load_lds_dwordx4 v[194:195], off
	s_add_i32 m0, s18, 0x2000
	s_add_u32 s38, s56, 0x40080
	v_lshl_add_u64 v[194:195], v[218:219], 0, s[30:31]
	s_addc_u32 s39, s57, 0
	s_add_i32 s18, s83, s27
	global_load_lds_dwordx4 v[194:195], off
	v_lshl_add_u64 v[194:195], s[38:39], 0, v[0:1]
	s_mov_b32 m0, s18
	s_nop 0
	global_load_lds_dwordx4 v[194:195], off
	v_lshl_add_u64 v[194:195], s[38:39], 0, v[130:131]
	s_add_i32 m0, s18, 0x2000
	s_nop 0
	global_load_lds_dwordx4 v[194:195], off
	v_lshl_add_u64 v[194:195], v[220:221], 0, s[30:31]
	s_mov_b32 m0, s71
	s_nop 0
	global_load_lds_dwordx4 v[194:195], off
	v_lshl_add_u64 v[194:195], v[222:223], 0, s[30:31]
	s_mov_b32 m0, s72
	s_nop 0
	global_load_lds_dwordx4 v[194:195], off
	s_waitcnt vmcnt(8)
	s_waitcnt lgkmcnt(0)
	s_barrier
	s_setprio 1
	s_waitcnt lgkmcnt(0)
	v_mfma_f32_16x16x32_bf16 v[50:53], v[146:149], v[178:181], v[50:53]
	v_mfma_f32_16x16x32_bf16 v[34:37], v[146:149], v[186:189], v[34:37]
	v_mfma_f32_16x16x32_bf16 v[18:21], v[146:149], v[202:205], v[18:21]
	v_mfma_f32_16x16x32_bf16 v[2:5], v[146:149], v[210:213], v[2:5]
	v_mfma_f32_16x16x32_bf16 v[54:57], v[154:157], v[178:181], v[54:57]
	v_mfma_f32_16x16x32_bf16 v[38:41], v[154:157], v[186:189], v[38:41]
	v_mfma_f32_16x16x32_bf16 v[22:25], v[154:157], v[202:205], v[22:25]
	v_mfma_f32_16x16x32_bf16 v[6:9], v[154:157], v[210:213], v[6:9]
	v_mfma_f32_16x16x32_bf16 v[50:53], v[150:153], v[182:185], v[50:53]
	v_mfma_f32_16x16x32_bf16 v[34:37], v[150:153], v[190:193], v[34:37]
	v_mfma_f32_16x16x32_bf16 v[18:21], v[150:153], v[206:209], v[18:21]
	v_mfma_f32_16x16x32_bf16 v[2:5], v[150:153], v[214:217], v[2:5]
	v_mfma_f32_16x16x32_bf16 v[54:57], v[158:161], v[182:185], v[54:57]
	v_mfma_f32_16x16x32_bf16 v[38:41], v[158:161], v[190:193], v[38:41]
	v_mfma_f32_16x16x32_bf16 v[22:25], v[158:161], v[206:209], v[22:25]
	v_mfma_f32_16x16x32_bf16 v[6:9], v[158:161], v[214:217], v[6:9]
	s_setprio 0
	s_setprio 1
	v_mfma_f32_16x16x32_bf16 v[58:61], v[162:165], v[178:181], v[58:61]
	v_mfma_f32_16x16x32_bf16 v[42:45], v[162:165], v[186:189], v[42:45]
	v_mfma_f32_16x16x32_bf16 v[26:29], v[162:165], v[202:205], v[26:29]
	v_mfma_f32_16x16x32_bf16 v[10:13], v[162:165], v[210:213], v[10:13]
	v_mfma_f32_16x16x32_bf16 v[62:65], v[170:173], v[178:181], v[62:65]
	v_mfma_f32_16x16x32_bf16 v[46:49], v[170:173], v[186:189], v[46:49]
	v_mfma_f32_16x16x32_bf16 v[30:33], v[170:173], v[202:205], v[30:33]
	v_mfma_f32_16x16x32_bf16 v[14:17], v[170:173], v[210:213], v[14:17]
	v_mfma_f32_16x16x32_bf16 v[58:61], v[166:169], v[182:185], v[58:61]
	v_mfma_f32_16x16x32_bf16 v[42:45], v[166:169], v[190:193], v[42:45]
	v_mfma_f32_16x16x32_bf16 v[26:29], v[166:169], v[206:209], v[26:29]
	v_mfma_f32_16x16x32_bf16 v[10:13], v[166:169], v[214:217], v[10:13]
	v_mfma_f32_16x16x32_bf16 v[62:65], v[174:177], v[182:185], v[62:65]
	v_mfma_f32_16x16x32_bf16 v[46:49], v[174:177], v[190:193], v[46:49]
	v_mfma_f32_16x16x32_bf16 v[30:33], v[174:177], v[206:209], v[30:33]
	v_mfma_f32_16x16x32_bf16 v[14:17], v[174:177], v[214:217], v[14:17]
	s_setprio 0
	s_barrier
	s_add_i32 s82, s82, 2
	s_add_u32 s60, s60, 0x100
	s_addc_u32 s61, s61, 0
	s_add_u32 s80, s80, 0x100
	s_addc_u32 s81, s81, 0
	s_cmp_gt_u32 s82, 13
	s_cbranch_scc0 .LBB0_220
	s_and_b64 vcc, exec, s[44:45]
	s_cbranch_vccz .LBB0_223
	s_barrier

; #define PG8_STAGE(bufoff, gbase, voff) do { _Pragma("unroll") for (int _i = 0; _i < 2; ++_i) \
;         __builtin_amdgcn_global_load_lds((const unsigned*)((const char*)(gbase) + (voff)[_i]), (PG8_LAS unsigned*)(lds + (bufoff) + ldsw + _i * 8192), 16, 0, 0); } while (0)
; #define PG8_LDA(dst, b, h) do { _Pragma("unroll") for (int m = 0; m < 4; ++m) _Pragma("unroll") for (int k = 0; k < 2; ++k) dst[m][k] = *(const PG8_LAS bf16x8*)(lds + PG8_SA(b, h) + aoff + m * 2048 + k * 1024); } while (0)
; #define PG8_LDB(dst, b, h) do { _Pragma("unroll") for (int n = 0; n < 2; ++n) _Pragma("unroll") for (int k = 0; k < 2; ++k) dst[n][k] = *(const PG8_LAS bf16x8*)(lds + PG8_SB(b, h) + boff + n * 2048 + k * 1024); } while (0)
; #define PG8_MMA(ai, bj, At, Bt) do { __builtin_amdgcn_s_setprio(1); _Pragma("unroll") for (int m = 0; m < 4; ++m) _Pragma("unroll") for (int n = 0; n < 2; ++n) _Pragma("unroll") for (int k = 0; k < 2; ++k) \
;         acc[ai][bj][m][n] = __builtin_amdgcn_mfma_f32_16x16x32_bf16(Bt[n][k], At[m][k], acc[ai][bj][m][n], 0, 0, 0); __builtin_amdgcn_s_setprio(0); } while (0)
; #define PG8_WAIT_V(n) asm volatile("s_waitcnt vmcnt(" #n ")" ::: "memory")
; #define PG8_WAIT_L(n) asm volatile("s_waitcnt lgkmcnt(" #n ")" ::: "memory")
; template <class Epi, class Sched, bool ALIGN_EPI = false, bool SP2 = false>
; __device__ __forceinline__ void gemm_phase(PG8_LAS unsigned char* lds, const Gemm g, const Sched& S, const Epi& E) {
;     ...
;             const bool last = (t == nt - 2);
;             const char* a1 = cA + (size_t)(t + 1) * kstep;
;             const char* a2 = last ? nA : cA + (size_t)(t + 2) * kstep; const char* b2 = last ? nB : cB + (size_t)(t + 2) * kstep;
;             const char* a3 = a2 + kstep; const char* b3 = b2 + kstep;
;             if (last && has_next) S.a_ready(nxt);
;             if constexpr (SP2) {
;             PG8_LDB(B0, 0, 0); PG8_LDB(B1, 0, 1); PG8_SCHED; PG8_LDA(At, 0, 0); PG8_STAGE(PG8_SA(1, 1), a1 + hstep, voffA);
;             PG8_WAIT_V(8); PG8_WAIT_L(0); PG8_BAR; PG8_MMA(0, 0, At, B0); PG8_MMA(0, 1, At, B1); PG8_BAR; PG8_SCHED;
;             PG8_LDA(At, 0, 1); PG8_STAGE(PG8_SB(0, 0), b2, voffB); PG8_STAGE(PG8_SB(0, 1), b2 + hstep, voffB); PG8_STAGE(PG8_SA(0, 0), a2, voffA);
;             PG8_WAIT_V(8); PG8_WAIT_L(0); PG8_BAR; PG8_MMA(1, 0, At, B0); PG8_MMA(1, 1, At, B1); PG8_BAR; PG8_SCHED;
.LBB0_274:
	s_add_i32 vcc_lo, s46, 2
	s_add_u32 s38, s48, 0x80
	s_addc_u32 s39, s49, 0
	s_add_i32 vcc_hi, 0, 0x10000
	s_cmp_eq_u32 s99, s46
	s_cselect_b32 s47, s81, s39
	s_cselect_b32 s46, s80, s38
	s_cselect_b32 s39, s83, s51
	s_cselect_b32 s38, s82, s50
	s_add_i32 s18, 0, 0x14000
	v_add_u32_e32 v142, vcc_hi, v245
	v_add_u32_e32 v158, s18, v245
	ds_read_b128 v[110:113], v142
	ds_read_b128 v[118:121], v142 offset:1024
	ds_read_b128 v[138:141], v142 offset:2048
	ds_read_b128 v[142:145], v142 offset:3072
	ds_read_b128 v[146:149], v158
	ds_read_b128 v[150:153], v158 offset:1024
	ds_read_b128 v[154:157], v158 offset:2048
	ds_read_b128 v[158:161], v158 offset:3072
	v_lshl_add_u64 v[210:211], s[48:49], 0, v[206:207]
	s_add_i32 m0, s92, 0xc000
	ds_read_b128 v[162:165], v247
	ds_read_b128 v[166:169], v247 offset:1024
	ds_read_b128 v[170:173], v247 offset:2048
	ds_read_b128 v[174:177], v247 offset:3072
	ds_read_b128 v[178:181], v247 offset:4096
	ds_read_b128 v[182:185], v247 offset:5120
	ds_read_b128 v[186:189], v247 offset:6144
	ds_read_b128 v[190:193], v247 offset:7168
	global_load_lds_dwordx4 v[210:211], off
	v_lshl_add_u64 v[210:211], s[48:49], 0, v[208:209]
	s_add_i32 m0, s92, 0xe000
	s_nop 0
	global_load_lds_dwordx4 v[210:211], off
	s_waitcnt vmcnt(8)
	s_waitcnt lgkmcnt(0)
	s_barrier
	s_setprio 1
	s_waitcnt lgkmcnt(0)
	v_mfma_f32_16x16x32_bf16 v[130:133], v[110:113], v[162:165], v[130:133]
	v_mfma_f32_16x16x32_bf16 v[114:117], v[110:113], v[170:173], v[114:117]
	v_mfma_f32_16x16x32_bf16 v[94:97], v[110:113], v[178:181], v[94:97]
	v_mfma_f32_16x16x32_bf16 v[78:81], v[110:113], v[186:189], v[78:81]
	v_mfma_f32_16x16x32_bf16 v[134:137], v[138:141], v[162:165], v[134:137]
	v_mfma_f32_16x16x32_bf16 v[106:109], v[138:141], v[170:173], v[106:109]
	v_mfma_f32_16x16x32_bf16 v[90:93], v[138:141], v[178:181], v[90:93]
	v_mfma_f32_16x16x32_bf16 v[74:77], v[138:141], v[186:189], v[74:77]
	v_mfma_f32_16x16x32_bf16 v[130:133], v[118:121], v[166:169], v[130:133]
	v_mfma_f32_16x16x32_bf16 v[114:117], v[118:121], v[174:177], v[114:117]
	v_mfma_f32_16x16x32_bf16 v[94:97], v[118:121], v[182:185], v[94:97]
	v_mfma_f32_16x16x32_bf16 v[78:81], v[118:121], v[190:193], v[78:81]
	v_mfma_f32_16x16x32_bf16 v[134:137], v[142:145], v[166:169], v[134:137]
	v_mfma_f32_16x16x32_bf16 v[106:109], v[142:145], v[174:177], v[106:109]
	v_mfma_f32_16x16x32_bf16 v[90:93], v[142:145], v[182:185], v[90:93]
	v_mfma_f32_16x16x32_bf16 v[74:77], v[142:145], v[190:193], v[74:77]
	s_setprio 0
	s_setprio 1
	v_mfma_f32_16x16x32_bf16 v[126:129], v[146:149], v[162:165], v[126:129]
	v_mfma_f32_16x16x32_bf16 v[102:105], v[146:149], v[170:173], v[102:105]
	v_mfma_f32_16x16x32_bf16 v[86:89], v[146:149], v[178:181], v[86:89]
	v_mfma_f32_16x16x32_bf16 v[70:73], v[146:149], v[186:189], v[70:73]
	v_mfma_f32_16x16x32_bf16 v[122:125], v[154:157], v[162:165], v[122:125]
	v_mfma_f32_16x16x32_bf16 v[98:101], v[154:157], v[170:173], v[98:101]
	v_mfma_f32_16x16x32_bf16 v[82:85], v[154:157], v[178:181], v[82:85]
	v_mfma_f32_16x16x32_bf16 v[66:69], v[154:157], v[186:189], v[66:69]
	v_mfma_f32_16x16x32_bf16 v[126:129], v[150:153], v[166:169], v[126:129]
	v_mfma_f32_16x16x32_bf16 v[102:105], v[150:153], v[174:177], v[102:105]
	v_mfma_f32_16x16x32_bf16 v[86:89], v[150:153], v[182:185], v[86:89]
	v_mfma_f32_16x16x32_bf16 v[70:73], v[150:153], v[190:193], v[70:73]
	v_mfma_f32_16x16x32_bf16 v[122:125], v[158:161], v[166:169], v[122:125]
	v_mfma_f32_16x16x32_bf16 v[98:101], v[158:161], v[174:177], v[98:101]
	v_mfma_f32_16x16x32_bf16 v[82:85], v[158:161], v[182:185], v[82:85]
	v_mfma_f32_16x16x32_bf16 v[66:69], v[158:161], v[190:193], v[66:69]
	s_setprio 0
	s_barrier
	s_add_i32 vcc_hi, vcc_hi, s6
	v_lshl_add_u64 v[210:211], s[38:39], 0, v[0:1]
	s_mov_b32 m0, vcc_hi
	ds_read_b128 v[162:165], v247 offset:16384
	ds_read_b128 v[166:169], v247 offset:17408
	ds_read_b128 v[170:173], v247 offset:18432
	ds_read_b128 v[174:177], v247 offset:19456
	ds_read_b128 v[178:181], v247 offset:20480
	ds_read_b128 v[182:185], v247 offset:21504
	ds_read_b128 v[186:189], v247 offset:22528
	ds_read_b128 v[190:193], v247 offset:23552
	global_load_lds_dwordx4 v[210:211], off
	s_add_i32 m0, vcc_hi, 0x2000
	v_lshl_add_u64 v[212:213], s[38:39], 0, v[204:205]
	s_add_u32 s38, s38, s58
	s_addc_u32 s39, s39, 0
	s_add_i32 s18, s18, s6
	global_load_lds_dwordx4 v[212:213], off
	v_lshl_add_u64 v[214:215], s[38:39], 0, v[0:1]
	s_mov_b32 m0, s18
	v_lshl_add_u64 v[216:217], s[38:39], 0, v[204:205]
	global_load_lds_dwordx4 v[214:215], off
	s_add_i32 m0, s18, 0x2000
	v_lshl_add_u64 v[218:219], s[46:47], 0, v[194:195]
	global_load_lds_dwordx4 v[216:217], off
	s_mov_b32 m0, s92
	v_lshl_add_u64 v[220:221], s[46:47], 0, v[202:203]
	global_load_lds_dwordx4 v[218:219], off
	s_mov_b32 m0, s93
	s_nop 0
	global_load_lds_dwordx4 v[220:221], off
	s_waitcnt vmcnt(8)
	s_waitcnt lgkmcnt(0)
	s_barrier
; #define PG8_STAGE(bufoff, gbase, voff) do { _Pragma("unroll") for (int _i = 0; _i < 2; ++_i) \
;         __builtin_amdgcn_global_load_lds((const unsigned*)((const char*)(gbase) + (voff)[_i]), (PG8_LAS unsigned*)(lds + (bufoff) + ldsw + _i * 8192), 16, 0, 0); } while (0)
; #define PG8_LDA(dst, b, h) do { _Pragma("unroll") for (int m = 0; m < 4; ++m) _Pragma("unroll") for (int k = 0; k < 2; ++k) dst[m][k] = *(const PG8_LAS bf16x8*)(lds + PG8_SA(b, h) + aoff + m * 2048 + k * 1024); } while (0)
; #define PG8_LDB(dst, b, h) do { _Pragma("unroll") for (int n = 0; n < 2; ++n) _Pragma("unroll") for (int k = 0; k < 2; ++k) dst[n][k] = *(const PG8_LAS bf16x8*)(lds + PG8_SB(b, h) + boff + n * 2048 + k * 1024); } while (0)
; #define PG8_MMA(ai, bj, At, Bt) do { __builtin_amdgcn_s_setprio(1); _Pragma("unroll") for (int m = 0; m < 4; ++m) _Pragma("unroll") for (int n = 0; n < 2; ++n) _Pragma("unroll") for (int k = 0; k < 2; ++k) \
;         acc[ai][bj][m][n] = __builtin_amdgcn_mfma_f32_16x16x32_bf16(Bt[n][k], At[m][k], acc[ai][bj][m][n], 0, 0, 0); __builtin_amdgcn_s_setprio(0); } while (0)
; #define PG8_WAIT_V(n) asm volatile("s_waitcnt vmcnt(" #n ")" ::: "memory")
; #define PG8_WAIT_L(n) asm volatile("s_waitcnt lgkmcnt(" #n ")" ::: "memory")
; #define PG8_BAR __builtin_amdgcn_s_barrier()
; #define PG8_SCHED __builtin_amdgcn_sched_barrier(0)
; template <class Epi, class Sched, bool ALIGN_EPI = false, bool SP2 = false>
; __device__ __forceinline__ void gemm_phase(PG8_LAS unsigned char* lds, const Gemm g, const Sched& S, const Epi& E) {
;     ...
;             PG8_WAIT_V(8); PG8_WAIT_L(0); PG8_BAR; PG8_MMA(1, 0, At, B0); PG8_MMA(1, 1, At, B1); PG8_BAR; PG8_SCHED;
;             PG8_LDB(B0, 1, 0); PG8_LDB(B1, 1, 1); PG8_SCHED; PG8_LDA(At, 1, 0); PG8_STAGE(PG8_SA(0, 1), a2 + hstep, voffA);
;             PG8_WAIT_V(8); PG8_WAIT_L(0); PG8_BAR; PG8_MMA(0, 0, At, B0); PG8_MMA(0, 1, At, B1); PG8_BAR; PG8_SCHED;
	s_setprio 1
	s_waitcnt lgkmcnt(0)
	v_mfma_f32_16x16x32_bf16 v[62:65], v[110:113], v[162:165], v[62:65]
	v_mfma_f32_16x16x32_bf16 v[46:49], v[110:113], v[170:173], v[46:49]
	v_mfma_f32_16x16x32_bf16 v[30:33], v[110:113], v[178:181], v[30:33]
	v_mfma_f32_16x16x32_bf16 v[14:17], v[110:113], v[186:189], v[14:17]
	v_mfma_f32_16x16x32_bf16 v[58:61], v[138:141], v[162:165], v[58:61]
	v_mfma_f32_16x16x32_bf16 v[42:45], v[138:141], v[170:173], v[42:45]
	v_mfma_f32_16x16x32_bf16 v[26:29], v[138:141], v[178:181], v[26:29]
	v_mfma_f32_16x16x32_bf16 v[10:13], v[138:141], v[186:189], v[10:13]
	v_mfma_f32_16x16x32_bf16 v[62:65], v[118:121], v[166:169], v[62:65]
	v_mfma_f32_16x16x32_bf16 v[46:49], v[118:121], v[174:177], v[46:49]
	v_mfma_f32_16x16x32_bf16 v[30:33], v[118:121], v[182:185], v[30:33]
	v_mfma_f32_16x16x32_bf16 v[14:17], v[118:121], v[190:193], v[14:17]
	v_mfma_f32_16x16x32_bf16 v[58:61], v[142:145], v[166:169], v[58:61]
	v_mfma_f32_16x16x32_bf16 v[42:45], v[142:145], v[174:177], v[42:45]
	v_mfma_f32_16x16x32_bf16 v[26:29], v[142:145], v[182:185], v[26:29]
	v_mfma_f32_16x16x32_bf16 v[10:13], v[142:145], v[190:193], v[10:13]
	s_setprio 0
	s_setprio 1
	v_mfma_f32_16x16x32_bf16 v[54:57], v[146:149], v[162:165], v[54:57]
	v_mfma_f32_16x16x32_bf16 v[38:41], v[146:149], v[170:173], v[38:41]
	v_mfma_f32_16x16x32_bf16 v[22:25], v[146:149], v[178:181], v[22:25]
	v_mfma_f32_16x16x32_bf16 v[6:9], v[146:149], v[186:189], v[6:9]
	v_mfma_f32_16x16x32_bf16 v[50:53], v[154:157], v[162:165], v[50:53]
	v_mfma_f32_16x16x32_bf16 v[34:37], v[154:157], v[170:173], v[34:37]
	v_mfma_f32_16x16x32_bf16 v[18:21], v[154:157], v[178:181], v[18:21]
	v_mfma_f32_16x16x32_bf16 v[2:5], v[154:157], v[186:189], v[2:5]
	v_mfma_f32_16x16x32_bf16 v[54:57], v[150:153], v[166:169], v[54:57]
	v_mfma_f32_16x16x32_bf16 v[38:41], v[150:153], v[174:177], v[38:41]
	v_mfma_f32_16x16x32_bf16 v[22:25], v[150:153], v[182:185], v[22:25]
	v_mfma_f32_16x16x32_bf16 v[6:9], v[150:153], v[190:193], v[6:9]
	v_mfma_f32_16x16x32_bf16 v[50:53], v[158:161], v[166:169], v[50:53]
	v_mfma_f32_16x16x32_bf16 v[34:37], v[158:161], v[174:177], v[34:37]
	v_mfma_f32_16x16x32_bf16 v[18:21], v[158:161], v[182:185], v[18:21]
	v_mfma_f32_16x16x32_bf16 v[2:5], v[158:161], v[190:193], v[2:5]
	s_setprio 0
	s_barrier
	s_add_i32 s18, 0, 0x18000
	s_add_i32 vcc_hi, 0, 0x1c000
	v_add_u32_e32 v142, s18, v245
	v_add_u32_e32 v158, vcc_hi, v245
	ds_read_b128 v[110:113], v142
	ds_read_b128 v[118:121], v142 offset:1024
	ds_read_b128 v[138:141], v142 offset:2048
	ds_read_b128 v[142:145], v142 offset:3072
	ds_read_b128 v[146:149], v158
	ds_read_b128 v[150:153], v158 offset:1024
	ds_read_b128 v[154:157], v158 offset:2048
	ds_read_b128 v[158:161], v158 offset:3072
	s_add_u32 s38, s46, s58
	s_addc_u32 s39, s47, 0
	s_mov_b32 m0, s94
	v_lshl_add_u64 v[222:223], s[38:39], 0, v[194:195]
	ds_read_b128 v[162:165], v247 offset:32768
	ds_read_b128 v[166:169], v247 offset:33792
	ds_read_b128 v[170:173], v247 offset:34816
	ds_read_b128 v[174:177], v247 offset:35840
	ds_read_b128 v[178:181], v247 offset:36864
	ds_read_b128 v[182:185], v247 offset:37888
	ds_read_b128 v[186:189], v247 offset:38912
	ds_read_b128 v[190:193], v247 offset:39936
	global_load_lds_dwordx4 v[222:223], off
	v_lshl_add_u64 v[222:223], s[38:39], 0, v[202:203]
	s_mov_b32 m0, s95
	s_nop 0
	global_load_lds_dwordx4 v[222:223], off
	s_waitcnt vmcnt(8)
	s_waitcnt lgkmcnt(0)
	s_barrier
	s_setprio 1
	s_waitcnt lgkmcnt(0)
	v_mfma_f32_16x16x32_bf16 v[130:133], v[110:113], v[162:165], v[130:133]
	v_mfma_f32_16x16x32_bf16 v[114:117], v[110:113], v[170:173], v[114:117]
	v_mfma_f32_16x16x32_bf16 v[94:97], v[110:113], v[178:181], v[94:97]
	v_mfma_f32_16x16x32_bf16 v[78:81], v[110:113], v[186:189], v[78:81]
	v_mfma_f32_16x16x32_bf16 v[134:137], v[138:141], v[162:165], v[134:137]
	v_mfma_f32_16x16x32_bf16 v[106:109], v[138:141], v[170:173], v[106:109]
	v_mfma_f32_16x16x32_bf16 v[90:93], v[138:141], v[178:181], v[90:93]
	v_mfma_f32_16x16x32_bf16 v[74:77], v[138:141], v[186:189], v[74:77]
	v_mfma_f32_16x16x32_bf16 v[130:133], v[118:121], v[166:169], v[130:133]
	v_mfma_f32_16x16x32_bf16 v[114:117], v[118:121], v[174:177], v[114:117]
	v_mfma_f32_16x16x32_bf16 v[94:97], v[118:121], v[182:185], v[94:97]
	v_mfma_f32_16x16x32_bf16 v[78:81], v[118:121], v[190:193], v[78:81]
	v_mfma_f32_16x16x32_bf16 v[134:137], v[142:145], v[166:169], v[134:137]
	v_mfma_f32_16x16x32_bf16 v[106:109], v[142:145], v[174:177], v[106:109]
	v_mfma_f32_16x16x32_bf16 v[90:93], v[142:145], v[182:185], v[90:93]
	v_mfma_f32_16x16x32_bf16 v[74:77], v[142:145], v[190:193], v[74:77]
	s_setprio 0
	s_setprio 1
	v_mfma_f32_16x16x32_bf16 v[126:129], v[146:149], v[162:165], v[126:129]
	v_mfma_f32_16x16x32_bf16 v[102:105], v[146:149], v[170:173], v[102:105]
	v_mfma_f32_16x16x32_bf16 v[86:89], v[146:149], v[178:181], v[86:89]
	v_mfma_f32_16x16x32_bf16 v[70:73], v[146:149], v[186:189], v[70:73]
	v_mfma_f32_16x16x32_bf16 v[122:125], v[154:157], v[162:165], v[122:125]
	v_mfma_f32_16x16x32_bf16 v[98:101], v[154:157], v[170:173], v[98:101]
	v_mfma_f32_16x16x32_bf16 v[82:85], v[154:157], v[178:181], v[82:85]
	v_mfma_f32_16x16x32_bf16 v[66:69], v[154:157], v[186:189], v[66:69]
	v_mfma_f32_16x16x32_bf16 v[126:129], v[150:153], v[166:169], v[126:129]
	v_mfma_f32_16x16x32_bf16 v[102:105], v[150:153], v[174:177], v[102:105]
	v_mfma_f32_16x16x32_bf16 v[86:89], v[150:153], v[182:185], v[86:89]
	v_mfma_f32_16x16x32_bf16 v[70:73], v[150:153], v[190:193], v[70:73]
	v_mfma_f32_16x16x32_bf16 v[122:125], v[158:161], v[166:169], v[122:125]
	v_mfma_f32_16x16x32_bf16 v[98:101], v[158:161], v[174:177], v[98:101]
	v_mfma_f32_16x16x32_bf16 v[82:85], v[158:161], v[182:185], v[82:85]
	v_mfma_f32_16x16x32_bf16 v[66:69], v[158:161], v[190:193], v[66:69]
	s_setprio 0
	s_barrier
; #define PG8_STAGE(bufoff, gbase, voff) do { _Pragma("unroll") for (int _i = 0; _i < 2; ++_i) \
;         __builtin_amdgcn_global_load_lds((const unsigned*)((const char*)(gbase) + (voff)[_i]), (PG8_LAS unsigned*)(lds + (bufoff) + ldsw + _i * 8192), 16, 0, 0); } while (0)
; #define PG8_LDA(dst, b, h) do { _Pragma("unroll") for (int m = 0; m < 4; ++m) _Pragma("unroll") for (int k = 0; k < 2; ++k) dst[m][k] = *(const PG8_LAS bf16x8*)(lds + PG8_SA(b, h) + aoff + m * 2048 + k * 1024); } while (0)
; #define PG8_MMA(ai, bj, At, Bt) do { __builtin_amdgcn_s_setprio(1); _Pragma("unroll") for (int m = 0; m < 4; ++m) _Pragma("unroll") for (int n = 0; n < 2; ++n) _Pragma("unroll") for (int k = 0; k < 2; ++k) \
;         acc[ai][bj][m][n] = __builtin_amdgcn_mfma_f32_16x16x32_bf16(Bt[n][k], At[m][k], acc[ai][bj][m][n], 0, 0, 0); __builtin_amdgcn_s_setprio(0); } while (0)
; #define PG8_WAIT_V(n) asm volatile("s_waitcnt vmcnt(" #n ")" ::: "memory")
; #define PG8_WAIT_L(n) asm volatile("s_waitcnt lgkmcnt(" #n ")" ::: "memory")
; #define PG8_BAR __builtin_amdgcn_s_barrier()
; #define PG8_SCHED __builtin_amdgcn_sched_barrier(0)
; template <class Epi, class Sched, bool ALIGN_EPI = false, bool SP2 = false>
; __device__ __forceinline__ void gemm_phase(PG8_LAS unsigned char* lds, const Gemm g, const Sched& S, const Epi& E) {
;     ...
;         for (int t = 0; t < nt; t += 2) {
;             const bool last = (t == nt - 2);
;             const char* a1 = cA + (size_t)(t + 1) * kstep;
;             const char* a2 = last ? nA : cA + (size_t)(t + 2) * kstep; const char* b2 = last ? nB : cB + (size_t)(t + 2) * kstep;
;             const char* a3 = a2 + kstep; const char* b3 = b2 + kstep;
;             if (last && has_next) S.a_ready(nxt);
;     ...
;             PG8_LDA(At, 1, 1); PG8_STAGE(PG8_SB(1, 0), b3, voffB); PG8_STAGE(PG8_SB(1, 1), b3 + hstep, voffB); PG8_STAGE(PG8_SA(1, 0), a3, voffA);
;             PG8_WAIT_V(8); PG8_WAIT_L(0); PG8_BAR; PG8_MMA(1, 0, At, B0); PG8_MMA(1, 1, At, B1); PG8_BAR; PG8_SCHED;
	s_add_i32 s18, s18, s6
	v_lshl_add_u64 v[210:211], v[210:211], 0, s[30:31]
	s_mov_b32 m0, s18
	ds_read_b128 v[162:165], v247 offset:49152
	ds_read_b128 v[166:169], v247 offset:50176
	ds_read_b128 v[170:173], v247 offset:51200
	ds_read_b128 v[174:177], v247 offset:52224
	ds_read_b128 v[178:181], v247 offset:53248
	ds_read_b128 v[182:185], v247 offset:54272
	ds_read_b128 v[186:189], v247 offset:55296
	ds_read_b128 v[190:193], v247 offset:56320
	global_load_lds_dwordx4 v[210:211], off
	v_lshl_add_u64 v[210:211], v[212:213], 0, s[30:31]
	s_add_i32 m0, s18, 0x2000
	s_add_i32 s18, vcc_hi, s6
	global_load_lds_dwordx4 v[210:211], off
	v_lshl_add_u64 v[210:211], v[214:215], 0, s[30:31]
	s_mov_b32 m0, s18
	s_nop 0
	global_load_lds_dwordx4 v[210:211], off
	v_lshl_add_u64 v[210:211], v[216:217], 0, s[30:31]
	s_add_i32 m0, s18, 0x2000
	s_nop 0
	global_load_lds_dwordx4 v[210:211], off
	v_lshl_add_u64 v[210:211], v[218:219], 0, s[30:31]
	s_mov_b32 m0, s97
	s_nop 0
	global_load_lds_dwordx4 v[210:211], off
	v_lshl_add_u64 v[210:211], v[220:221], 0, s[30:31]
	s_mov_b32 m0, s98
	s_nop 0
	global_load_lds_dwordx4 v[210:211], off
	s_waitcnt vmcnt(8)
	s_waitcnt lgkmcnt(0)
	s_barrier
	s_setprio 1
	s_waitcnt lgkmcnt(0)
	v_mfma_f32_16x16x32_bf16 v[62:65], v[110:113], v[162:165], v[62:65]
	v_mfma_f32_16x16x32_bf16 v[46:49], v[110:113], v[170:173], v[46:49]
	v_mfma_f32_16x16x32_bf16 v[30:33], v[110:113], v[178:181], v[30:33]
	v_mfma_f32_16x16x32_bf16 v[14:17], v[110:113], v[186:189], v[14:17]
	v_mfma_f32_16x16x32_bf16 v[58:61], v[138:141], v[162:165], v[58:61]
	v_mfma_f32_16x16x32_bf16 v[42:45], v[138:141], v[170:173], v[42:45]
	v_mfma_f32_16x16x32_bf16 v[26:29], v[138:141], v[178:181], v[26:29]
	v_mfma_f32_16x16x32_bf16 v[10:13], v[138:141], v[186:189], v[10:13]
	v_mfma_f32_16x16x32_bf16 v[62:65], v[118:121], v[166:169], v[62:65]
	v_mfma_f32_16x16x32_bf16 v[46:49], v[118:121], v[174:177], v[46:49]
	v_mfma_f32_16x16x32_bf16 v[30:33], v[118:121], v[182:185], v[30:33]
	v_mfma_f32_16x16x32_bf16 v[14:17], v[118:121], v[190:193], v[14:17]
	v_mfma_f32_16x16x32_bf16 v[58:61], v[142:145], v[166:169], v[58:61]
	v_mfma_f32_16x16x32_bf16 v[42:45], v[142:145], v[174:177], v[42:45]
	v_mfma_f32_16x16x32_bf16 v[26:29], v[142:145], v[182:185], v[26:29]
	v_mfma_f32_16x16x32_bf16 v[10:13], v[142:145], v[190:193], v[10:13]
	s_setprio 0
	s_setprio 1
	v_mfma_f32_16x16x32_bf16 v[54:57], v[146:149], v[162:165], v[54:57]
	v_mfma_f32_16x16x32_bf16 v[38:41], v[146:149], v[170:173], v[38:41]
	v_mfma_f32_16x16x32_bf16 v[22:25], v[146:149], v[178:181], v[22:25]
	v_mfma_f32_16x16x32_bf16 v[6:9], v[146:149], v[186:189], v[6:9]
	v_mfma_f32_16x16x32_bf16 v[50:53], v[154:157], v[162:165], v[50:53]
	v_mfma_f32_16x16x32_bf16 v[34:37], v[154:157], v[170:173], v[34:37]
	v_mfma_f32_16x16x32_bf16 v[18:21], v[154:157], v[178:181], v[18:21]
	v_mfma_f32_16x16x32_bf16 v[2:5], v[154:157], v[186:189], v[2:5]
	v_mfma_f32_16x16x32_bf16 v[54:57], v[150:153], v[166:169], v[54:57]
	v_mfma_f32_16x16x32_bf16 v[38:41], v[150:153], v[174:177], v[38:41]
	v_mfma_f32_16x16x32_bf16 v[22:25], v[150:153], v[182:185], v[22:25]
	v_mfma_f32_16x16x32_bf16 v[6:9], v[150:153], v[190:193], v[6:9]
	v_mfma_f32_16x16x32_bf16 v[50:53], v[158:161], v[166:169], v[50:53]
	v_mfma_f32_16x16x32_bf16 v[34:37], v[158:161], v[174:177], v[34:37]
	v_mfma_f32_16x16x32_bf16 v[18:21], v[158:161], v[182:185], v[18:21]
	v_mfma_f32_16x16x32_bf16 v[2:5], v[158:161], v[190:193], v[2:5]
	s_setprio 0
	s_barrier
	s_add_u32 s48, s48, 0x100
	s_addc_u32 s49, s49, 0
	s_add_u32 s50, s50, 0x100
	s_addc_u32 s51, s51, 0
	s_cmp_ge_u32 vcc_lo, s96
	s_mov_b32 s46, vcc_lo
	s_cbranch_scc0 .LBB0_274
	s_and_b64 vcc, exec, s[72:73]
	s_cbranch_vccz .LBB0_277
	s_barrier

; #define PG8_STAGE(bufoff, gbase, voff) do { _Pragma("unroll") for (int _i = 0; _i < 2; ++_i) \
;         __builtin_amdgcn_global_load_lds((const unsigned*)((const char*)(gbase) + (voff)[_i]), (PG8_LAS unsigned*)(lds + (bufoff) + ldsw + _i * 8192), 16, 0, 0); } while (0)
; #define PG8_LDA(dst, b, h) do { _Pragma("unroll") for (int m = 0; m < 4; ++m) _Pragma("unroll") for (int k = 0; k < 2; ++k) dst[m][k] = *(const PG8_LAS bf16x8*)(lds + PG8_SA(b, h) + aoff + m * 2048 + k * 1024); } while (0)
; #define PG8_LDB(dst, b, h) do { _Pragma("unroll") for (int n = 0; n < 2; ++n) _Pragma("unroll") for (int k = 0; k < 2; ++k) dst[n][k] = *(const PG8_LAS bf16x8*)(lds + PG8_SB(b, h) + boff + n * 2048 + k * 1024); } while (0)
; #define PG8_MMA(ai, bj, At, Bt) do { __builtin_amdgcn_s_setprio(1); _Pragma("unroll") for (int m = 0; m < 4; ++m) _Pragma("unroll") for (int n = 0; n < 2; ++n) _Pragma("unroll") for (int k = 0; k < 2; ++k) \
;         acc[ai][bj][m][n] = __builtin_amdgcn_mfma_f32_16x16x32_bf16(Bt[n][k], At[m][k], acc[ai][bj][m][n], 0, 0, 0); __builtin_amdgcn_s_setprio(0); } while (0)
; #define PG8_WAIT_V(n) asm volatile("s_waitcnt vmcnt(" #n ")" ::: "memory")
; #define PG8_WAIT_L(n) asm volatile("s_waitcnt lgkmcnt(" #n ")" ::: "memory")
; template <class Epi, class Sched, bool ALIGN_EPI = false, bool SP2 = false>
; __device__ __forceinline__ void gemm_phase(PG8_LAS unsigned char* lds, const Gemm g, const Sched& S, const Epi& E) {
;     ...
;             const bool last = (t == nt - 2);
;             const char* a1 = cA + (size_t)(t + 1) * kstep;
;             const char* a2 = last ? nA : cA + (size_t)(t + 2) * kstep; const char* b2 = last ? nB : cB + (size_t)(t + 2) * kstep;
;             const char* a3 = a2 + kstep; const char* b3 = b2 + kstep;
;             if (last && has_next) S.a_ready(nxt);
;             if constexpr (SP2) {
;             PG8_LDB(B0, 0, 0); PG8_LDB(B1, 0, 1); PG8_SCHED; PG8_LDA(At, 0, 0); PG8_STAGE(PG8_SA(1, 1), a1 + hstep, voffA);
;             PG8_WAIT_V(8); PG8_WAIT_L(0); PG8_BAR; PG8_MMA(0, 0, At, B0); PG8_MMA(0, 1, At, B1); PG8_BAR; PG8_SCHED;
;             PG8_LDA(At, 0, 1); PG8_STAGE(PG8_SB(0, 0), b2, voffB); PG8_STAGE(PG8_SB(0, 1), b2 + hstep, voffB); PG8_STAGE(PG8_SA(0, 0), a2, voffA);
;             PG8_WAIT_V(8); PG8_WAIT_L(0); PG8_BAR; PG8_MMA(1, 0, At, B0); PG8_MMA(1, 1, At, B1); PG8_BAR; PG8_SCHED;
.LBB0_408:
	s_add_u32 s38, s48, 0xfffc0080
	s_addc_u32 s39, s49, -1
	s_add_i32 s85, 0, 0x10000
	s_cmp_eq_u32 s84, 12
	s_cselect_b32 s73, s21, s39
	s_cselect_b32 s72, s27, s38
	v_add_u32_e32 v0, s85, v167
	s_cselect_b32 s47, s29, s69
	s_cselect_b32 s46, s33, s53
	s_add_i32 s38, 0, 0x14000
	ds_read_b128 v[142:145], v0
	ds_read_b128 v[146:149], v0 offset:1024
	ds_read_b128 v[150:153], v0 offset:2048
	ds_read_b128 v[154:157], v0 offset:3072
	v_add_u32_e32 v0, s38, v167
	ds_read_b128 v[158:161], v0
	ds_read_b128 v[162:165], v0 offset:1024
	ds_read_b128 v[172:175], v0 offset:2048
	ds_read_b128 v[176:179], v0 offset:3072
	v_lshl_add_u64 v[218:219], s[48:49], 0, v[138:139]
	s_add_i32 m0, s76, 0xc000
	ds_read_b128 v[180:183], v170
	ds_read_b128 v[184:187], v170 offset:1024
	ds_read_b128 v[188:191], v170 offset:2048
	ds_read_b128 v[192:195], v170 offset:3072
	ds_read_b128 v[202:205], v170 offset:4096
	ds_read_b128 v[206:209], v170 offset:5120
	ds_read_b128 v[210:213], v170 offset:6144
	ds_read_b128 v[214:217], v170 offset:7168
	global_load_lds_dwordx4 v[218:219], off
	v_lshl_add_u64 v[218:219], s[48:49], 0, v[140:141]
	s_add_i32 m0, s76, 0xe000
	s_nop 0
	global_load_lds_dwordx4 v[218:219], off
	s_waitcnt vmcnt(8)
	s_waitcnt lgkmcnt(0)
	s_barrier
	s_setprio 1
	s_waitcnt lgkmcnt(0)
	v_mfma_f32_16x16x32_bf16 v[122:125], v[142:145], v[180:183], v[122:125]
	v_mfma_f32_16x16x32_bf16 v[106:109], v[142:145], v[188:191], v[106:109]
	v_mfma_f32_16x16x32_bf16 v[90:93], v[142:145], v[202:205], v[90:93]
	v_mfma_f32_16x16x32_bf16 v[74:77], v[142:145], v[210:213], v[74:77]
	v_mfma_f32_16x16x32_bf16 v[126:129], v[150:153], v[180:183], v[126:129]
	v_mfma_f32_16x16x32_bf16 v[110:113], v[150:153], v[188:191], v[110:113]
	v_mfma_f32_16x16x32_bf16 v[94:97], v[150:153], v[202:205], v[94:97]
	v_mfma_f32_16x16x32_bf16 v[78:81], v[150:153], v[210:213], v[78:81]
	v_mfma_f32_16x16x32_bf16 v[122:125], v[146:149], v[184:187], v[122:125]
	v_mfma_f32_16x16x32_bf16 v[106:109], v[146:149], v[192:195], v[106:109]
	v_mfma_f32_16x16x32_bf16 v[90:93], v[146:149], v[206:209], v[90:93]
	v_mfma_f32_16x16x32_bf16 v[74:77], v[146:149], v[214:217], v[74:77]
	v_mfma_f32_16x16x32_bf16 v[126:129], v[154:157], v[184:187], v[126:129]
	v_mfma_f32_16x16x32_bf16 v[110:113], v[154:157], v[192:195], v[110:113]
	v_mfma_f32_16x16x32_bf16 v[94:97], v[154:157], v[206:209], v[94:97]
	v_mfma_f32_16x16x32_bf16 v[78:81], v[154:157], v[214:217], v[78:81]
	s_setprio 0
	s_setprio 1
	v_mfma_f32_16x16x32_bf16 v[114:117], v[158:161], v[180:183], v[114:117]
	v_mfma_f32_16x16x32_bf16 v[98:101], v[158:161], v[188:191], v[98:101]
	v_mfma_f32_16x16x32_bf16 v[82:85], v[158:161], v[202:205], v[82:85]
	v_mfma_f32_16x16x32_bf16 v[66:69], v[158:161], v[210:213], v[66:69]
	v_mfma_f32_16x16x32_bf16 v[118:121], v[172:175], v[180:183], v[118:121]
	v_mfma_f32_16x16x32_bf16 v[102:105], v[172:175], v[188:191], v[102:105]
	v_mfma_f32_16x16x32_bf16 v[86:89], v[172:175], v[202:205], v[86:89]
	v_mfma_f32_16x16x32_bf16 v[70:73], v[172:175], v[210:213], v[70:73]
	v_mfma_f32_16x16x32_bf16 v[114:117], v[162:165], v[184:187], v[114:117]
	v_mfma_f32_16x16x32_bf16 v[98:101], v[162:165], v[192:195], v[98:101]
	v_mfma_f32_16x16x32_bf16 v[82:85], v[162:165], v[206:209], v[82:85]
	v_mfma_f32_16x16x32_bf16 v[66:69], v[162:165], v[214:217], v[66:69]
	v_mfma_f32_16x16x32_bf16 v[118:121], v[176:179], v[184:187], v[118:121]
	v_mfma_f32_16x16x32_bf16 v[102:105], v[176:179], v[192:195], v[102:105]
	v_mfma_f32_16x16x32_bf16 v[86:89], v[176:179], v[206:209], v[86:89]
	v_mfma_f32_16x16x32_bf16 v[70:73], v[176:179], v[214:217], v[70:73]
	s_setprio 0
	s_barrier
	s_add_i32 s39, s85, s75
	v_lshl_add_u64 v[218:219], s[46:47], 0, v[134:135]
	s_mov_b32 m0, s39
	ds_read_b128 v[180:183], v170 offset:16384
	ds_read_b128 v[184:187], v170 offset:17408
	ds_read_b128 v[188:191], v170 offset:18432
	ds_read_b128 v[192:195], v170 offset:19456
	ds_read_b128 v[202:205], v170 offset:20480
	ds_read_b128 v[206:209], v170 offset:21504
	ds_read_b128 v[210:213], v170 offset:22528
	ds_read_b128 v[214:217], v170 offset:23552
	global_load_lds_dwordx4 v[218:219], off
	s_add_i32 m0, s39, 0x2000
	s_add_u32 s92, s46, 0x40000
	v_lshl_add_u64 v[220:221], s[46:47], 0, v[130:131]
	s_addc_u32 s93, s47, 0
	s_add_i32 s38, s38, s75
	global_load_lds_dwordx4 v[220:221], off
	v_lshl_add_u64 v[222:223], s[92:93], 0, v[134:135]
	s_mov_b32 m0, s38
	v_lshl_add_u64 v[224:225], s[72:73], 0, v[132:133]
	global_load_lds_dwordx4 v[222:223], off
	v_lshl_add_u64 v[222:223], s[92:93], 0, v[130:131]
	s_add_i32 m0, s38, 0x2000
	s_nop 0
	global_load_lds_dwordx4 v[222:223], off
	v_lshl_add_u64 v[222:223], s[72:73], 0, v[136:137]
	s_mov_b32 m0, s76
	s_nop 0
	global_load_lds_dwordx4 v[222:223], off
	s_mov_b32 m0, s77
	s_nop 0
	global_load_lds_dwordx4 v[224:225], off
	s_waitcnt vmcnt(8)
	s_waitcnt lgkmcnt(0)
	s_barrier
; #define PG8_STAGE(bufoff, gbase, voff) do { _Pragma("unroll") for (int _i = 0; _i < 2; ++_i) \
;         __builtin_amdgcn_global_load_lds((const unsigned*)((const char*)(gbase) + (voff)[_i]), (PG8_LAS unsigned*)(lds + (bufoff) + ldsw + _i * 8192), 16, 0, 0); } while (0)
; #define PG8_LDA(dst, b, h) do { _Pragma("unroll") for (int m = 0; m < 4; ++m) _Pragma("unroll") for (int k = 0; k < 2; ++k) dst[m][k] = *(const PG8_LAS bf16x8*)(lds + PG8_SA(b, h) + aoff + m * 2048 + k * 1024); } while (0)
; #define PG8_LDB(dst, b, h) do { _Pragma("unroll") for (int n = 0; n < 2; ++n) _Pragma("unroll") for (int k = 0; k < 2; ++k) dst[n][k] = *(const PG8_LAS bf16x8*)(lds + PG8_SB(b, h) + boff + n * 2048 + k * 1024); } while (0)
; #define PG8_MMA(ai, bj, At, Bt) do { __builtin_amdgcn_s_setprio(1); _Pragma("unroll") for (int m = 0; m < 4; ++m) _Pragma("unroll") for (int n = 0; n < 2; ++n) _Pragma("unroll") for (int k = 0; k < 2; ++k) \
;         acc[ai][bj][m][n] = __builtin_amdgcn_mfma_f32_16x16x32_bf16(Bt[n][k], At[m][k], acc[ai][bj][m][n], 0, 0, 0); __builtin_amdgcn_s_setprio(0); } while (0)
; #define PG8_WAIT_V(n) asm volatile("s_waitcnt vmcnt(" #n ")" ::: "memory")
; #define PG8_WAIT_L(n) asm volatile("s_waitcnt lgkmcnt(" #n ")" ::: "memory")
; #define PG8_BAR __builtin_amdgcn_s_barrier()
; #define PG8_SCHED __builtin_amdgcn_sched_barrier(0)
; template <class Epi, class Sched, bool ALIGN_EPI = false, bool SP2 = false>
; __device__ __forceinline__ void gemm_phase(PG8_LAS unsigned char* lds, const Gemm g, const Sched& S, const Epi& E) {
;     ...
;             PG8_WAIT_V(8); PG8_WAIT_L(0); PG8_BAR; PG8_MMA(1, 0, At, B0); PG8_MMA(1, 1, At, B1); PG8_BAR; PG8_SCHED;
;             PG8_LDB(B0, 1, 0); PG8_LDB(B1, 1, 1); PG8_SCHED; PG8_LDA(At, 1, 0); PG8_STAGE(PG8_SA(0, 1), a2 + hstep, voffA);
;             PG8_WAIT_V(8); PG8_WAIT_L(0); PG8_BAR; PG8_MMA(0, 0, At, B0); PG8_MMA(0, 1, At, B1); PG8_BAR; PG8_SCHED;
	s_setprio 1
	s_waitcnt lgkmcnt(0)
	v_mfma_f32_16x16x32_bf16 v[58:61], v[142:145], v[180:183], v[58:61]
	v_mfma_f32_16x16x32_bf16 v[42:45], v[142:145], v[188:191], v[42:45]
	v_mfma_f32_16x16x32_bf16 v[26:29], v[142:145], v[202:205], v[26:29]
	v_mfma_f32_16x16x32_bf16 v[10:13], v[142:145], v[210:213], v[10:13]
	v_mfma_f32_16x16x32_bf16 v[62:65], v[150:153], v[180:183], v[62:65]
	v_mfma_f32_16x16x32_bf16 v[46:49], v[150:153], v[188:191], v[46:49]
	v_mfma_f32_16x16x32_bf16 v[30:33], v[150:153], v[202:205], v[30:33]
	v_mfma_f32_16x16x32_bf16 v[14:17], v[150:153], v[210:213], v[14:17]
	v_mfma_f32_16x16x32_bf16 v[58:61], v[146:149], v[184:187], v[58:61]
	v_mfma_f32_16x16x32_bf16 v[42:45], v[146:149], v[192:195], v[42:45]
	v_mfma_f32_16x16x32_bf16 v[26:29], v[146:149], v[206:209], v[26:29]
	v_mfma_f32_16x16x32_bf16 v[10:13], v[146:149], v[214:217], v[10:13]
	v_mfma_f32_16x16x32_bf16 v[62:65], v[154:157], v[184:187], v[62:65]
	v_mfma_f32_16x16x32_bf16 v[46:49], v[154:157], v[192:195], v[46:49]
	v_mfma_f32_16x16x32_bf16 v[30:33], v[154:157], v[206:209], v[30:33]
	v_mfma_f32_16x16x32_bf16 v[14:17], v[154:157], v[214:217], v[14:17]
	s_setprio 0
	s_setprio 1
	v_mfma_f32_16x16x32_bf16 v[50:53], v[158:161], v[180:183], v[50:53]
	v_mfma_f32_16x16x32_bf16 v[34:37], v[158:161], v[188:191], v[34:37]
	v_mfma_f32_16x16x32_bf16 v[18:21], v[158:161], v[202:205], v[18:21]
	v_mfma_f32_16x16x32_bf16 v[2:5], v[158:161], v[210:213], v[2:5]
	v_mfma_f32_16x16x32_bf16 v[54:57], v[172:175], v[180:183], v[54:57]
	v_mfma_f32_16x16x32_bf16 v[38:41], v[172:175], v[188:191], v[38:41]
	v_mfma_f32_16x16x32_bf16 v[22:25], v[172:175], v[202:205], v[22:25]
	v_mfma_f32_16x16x32_bf16 v[6:9], v[172:175], v[210:213], v[6:9]
	v_mfma_f32_16x16x32_bf16 v[50:53], v[162:165], v[184:187], v[50:53]
	v_mfma_f32_16x16x32_bf16 v[34:37], v[162:165], v[192:195], v[34:37]
	v_mfma_f32_16x16x32_bf16 v[18:21], v[162:165], v[206:209], v[18:21]
	v_mfma_f32_16x16x32_bf16 v[2:5], v[162:165], v[214:217], v[2:5]
	v_mfma_f32_16x16x32_bf16 v[54:57], v[176:179], v[184:187], v[54:57]
	v_mfma_f32_16x16x32_bf16 v[38:41], v[176:179], v[192:195], v[38:41]
	v_mfma_f32_16x16x32_bf16 v[22:25], v[176:179], v[206:209], v[22:25]
	v_mfma_f32_16x16x32_bf16 v[6:9], v[176:179], v[214:217], v[6:9]
	s_setprio 0
	s_barrier
	s_add_i32 s38, 0, 0x18000
	v_add_u32_e32 v0, s38, v167
	s_add_i32 s39, 0, 0x1c000
	ds_read_b128 v[142:145], v0
	ds_read_b128 v[146:149], v0 offset:1024
	ds_read_b128 v[150:153], v0 offset:2048
	ds_read_b128 v[154:157], v0 offset:3072
	v_add_u32_e32 v0, s39, v167
	ds_read_b128 v[158:161], v0
	ds_read_b128 v[162:165], v0 offset:1024
	ds_read_b128 v[172:175], v0 offset:2048
	ds_read_b128 v[176:179], v0 offset:3072
	s_add_u32 s72, s72, 0x40000
	s_addc_u32 s73, s73, 0
	s_mov_b32 m0, s78
	v_lshl_add_u64 v[226:227], s[72:73], 0, v[136:137]
	ds_read_b128 v[180:183], v170 offset:32768
	ds_read_b128 v[184:187], v170 offset:33792
	ds_read_b128 v[188:191], v170 offset:34816
	ds_read_b128 v[192:195], v170 offset:35840
	ds_read_b128 v[202:205], v170 offset:36864
	ds_read_b128 v[206:209], v170 offset:37888
	ds_read_b128 v[210:213], v170 offset:38912
	ds_read_b128 v[214:217], v170 offset:39936
	global_load_lds_dwordx4 v[226:227], off
	v_lshl_add_u64 v[226:227], s[72:73], 0, v[132:133]
	s_mov_b32 m0, s79
	s_nop 0
	global_load_lds_dwordx4 v[226:227], off
	s_waitcnt vmcnt(8)
	s_waitcnt lgkmcnt(0)
	s_barrier
	s_setprio 1
	s_waitcnt lgkmcnt(0)
	v_mfma_f32_16x16x32_bf16 v[122:125], v[142:145], v[180:183], v[122:125]
	v_mfma_f32_16x16x32_bf16 v[106:109], v[142:145], v[188:191], v[106:109]
	v_mfma_f32_16x16x32_bf16 v[90:93], v[142:145], v[202:205], v[90:93]
	v_mfma_f32_16x16x32_bf16 v[74:77], v[142:145], v[210:213], v[74:77]
	v_mfma_f32_16x16x32_bf16 v[126:129], v[150:153], v[180:183], v[126:129]
	v_mfma_f32_16x16x32_bf16 v[110:113], v[150:153], v[188:191], v[110:113]
	v_mfma_f32_16x16x32_bf16 v[94:97], v[150:153], v[202:205], v[94:97]
	v_mfma_f32_16x16x32_bf16 v[78:81], v[150:153], v[210:213], v[78:81]
	v_mfma_f32_16x16x32_bf16 v[122:125], v[146:149], v[184:187], v[122:125]
	v_mfma_f32_16x16x32_bf16 v[106:109], v[146:149], v[192:195], v[106:109]
	v_mfma_f32_16x16x32_bf16 v[90:93], v[146:149], v[206:209], v[90:93]
	v_mfma_f32_16x16x32_bf16 v[74:77], v[146:149], v[214:217], v[74:77]
	v_mfma_f32_16x16x32_bf16 v[126:129], v[154:157], v[184:187], v[126:129]
	v_mfma_f32_16x16x32_bf16 v[110:113], v[154:157], v[192:195], v[110:113]
	v_mfma_f32_16x16x32_bf16 v[94:97], v[154:157], v[206:209], v[94:97]
	v_mfma_f32_16x16x32_bf16 v[78:81], v[154:157], v[214:217], v[78:81]
	s_setprio 0
	s_setprio 1
	v_mfma_f32_16x16x32_bf16 v[114:117], v[158:161], v[180:183], v[114:117]
	v_mfma_f32_16x16x32_bf16 v[98:101], v[158:161], v[188:191], v[98:101]
	v_mfma_f32_16x16x32_bf16 v[82:85], v[158:161], v[202:205], v[82:85]
	v_mfma_f32_16x16x32_bf16 v[66:69], v[158:161], v[210:213], v[66:69]
	v_mfma_f32_16x16x32_bf16 v[118:121], v[172:175], v[180:183], v[118:121]
	v_mfma_f32_16x16x32_bf16 v[102:105], v[172:175], v[188:191], v[102:105]
	v_mfma_f32_16x16x32_bf16 v[86:89], v[172:175], v[202:205], v[86:89]
	v_mfma_f32_16x16x32_bf16 v[70:73], v[172:175], v[210:213], v[70:73]
	v_mfma_f32_16x16x32_bf16 v[114:117], v[162:165], v[184:187], v[114:117]
	v_mfma_f32_16x16x32_bf16 v[98:101], v[162:165], v[192:195], v[98:101]
	v_mfma_f32_16x16x32_bf16 v[82:85], v[162:165], v[206:209], v[82:85]
	v_mfma_f32_16x16x32_bf16 v[66:69], v[162:165], v[214:217], v[66:69]
	v_mfma_f32_16x16x32_bf16 v[118:121], v[176:179], v[184:187], v[118:121]
	v_mfma_f32_16x16x32_bf16 v[102:105], v[176:179], v[192:195], v[102:105]
	v_mfma_f32_16x16x32_bf16 v[86:89], v[176:179], v[206:209], v[86:89]
	v_mfma_f32_16x16x32_bf16 v[70:73], v[176:179], v[214:217], v[70:73]
	s_setprio 0
	s_barrier
; #define PG8_STAGE(bufoff, gbase, voff) do { _Pragma("unroll") for (int _i = 0; _i < 2; ++_i) \
;         __builtin_amdgcn_global_load_lds((const unsigned*)((const char*)(gbase) + (voff)[_i]), (PG8_LAS unsigned*)(lds + (bufoff) + ldsw + _i * 8192), 16, 0, 0); } while (0)
; #define PG8_LDA(dst, b, h) do { _Pragma("unroll") for (int m = 0; m < 4; ++m) _Pragma("unroll") for (int k = 0; k < 2; ++k) dst[m][k] = *(const PG8_LAS bf16x8*)(lds + PG8_SA(b, h) + aoff + m * 2048 + k * 1024); } while (0)
; #define PG8_MMA(ai, bj, At, Bt) do { __builtin_amdgcn_s_setprio(1); _Pragma("unroll") for (int m = 0; m < 4; ++m) _Pragma("unroll") for (int n = 0; n < 2; ++n) _Pragma("unroll") for (int k = 0; k < 2; ++k) \
;         acc[ai][bj][m][n] = __builtin_amdgcn_mfma_f32_16x16x32_bf16(Bt[n][k], At[m][k], acc[ai][bj][m][n], 0, 0, 0); __builtin_amdgcn_s_setprio(0); } while (0)
; #define PG8_WAIT_V(n) asm volatile("s_waitcnt vmcnt(" #n ")" ::: "memory")
; #define PG8_WAIT_L(n) asm volatile("s_waitcnt lgkmcnt(" #n ")" ::: "memory")
; #define PG8_BAR __builtin_amdgcn_s_barrier()
; #define PG8_SCHED __builtin_amdgcn_sched_barrier(0)
; template <class Epi, class Sched, bool ALIGN_EPI = false, bool SP2 = false>
; __device__ __forceinline__ void gemm_phase(PG8_LAS unsigned char* lds, const Gemm g, const Sched& S, const Epi& E) {
;     ...
;         for (int t = 0; t < nt; t += 2) {
;             const bool last = (t == nt - 2);
;             const char* a1 = cA + (size_t)(t + 1) * kstep;
;             const char* a2 = last ? nA : cA + (size_t)(t + 2) * kstep; const char* b2 = last ? nB : cB + (size_t)(t + 2) * kstep;
;             const char* a3 = a2 + kstep; const char* b3 = b2 + kstep;
;             if (last && has_next) S.a_ready(nxt);
;     ...
;             PG8_LDA(At, 1, 1); PG8_STAGE(PG8_SB(1, 0), b3, voffB); PG8_STAGE(PG8_SB(1, 1), b3 + hstep, voffB); PG8_STAGE(PG8_SA(1, 0), a3, voffA);
;             PG8_WAIT_V(8); PG8_WAIT_L(0); PG8_BAR; PG8_MMA(1, 0, At, B0); PG8_MMA(1, 1, At, B1); PG8_BAR; PG8_SCHED;
	s_add_i32 s38, s38, s75
	v_lshl_add_u64 v[218:219], v[218:219], 0, s[30:31]
	s_mov_b32 m0, s38
	ds_read_b128 v[180:183], v170 offset:49152
	ds_read_b128 v[184:187], v170 offset:50176
	ds_read_b128 v[188:191], v170 offset:51200
	ds_read_b128 v[192:195], v170 offset:52224
	ds_read_b128 v[202:205], v170 offset:53248
	ds_read_b128 v[206:209], v170 offset:54272
	ds_read_b128 v[210:213], v170 offset:55296
	ds_read_b128 v[214:217], v170 offset:56320
	global_load_lds_dwordx4 v[218:219], off
	s_add_i32 m0, s38, 0x2000
	s_add_u32 s46, s46, 0x40080
	v_lshl_add_u64 v[218:219], v[220:221], 0, s[30:31]
	s_addc_u32 s47, s47, 0
	s_add_i32 s38, s39, s75
	global_load_lds_dwordx4 v[218:219], off
	v_lshl_add_u64 v[218:219], s[46:47], 0, v[134:135]
	s_mov_b32 m0, s38
	s_nop 0
	global_load_lds_dwordx4 v[218:219], off
	v_lshl_add_u64 v[218:219], s[46:47], 0, v[130:131]
	s_add_i32 m0, s38, 0x2000
	s_nop 0
	global_load_lds_dwordx4 v[218:219], off
	v_lshl_add_u64 v[218:219], v[222:223], 0, s[30:31]
	s_mov_b32 m0, s80
	s_nop 0
	global_load_lds_dwordx4 v[218:219], off
	v_lshl_add_u64 v[218:219], v[224:225], 0, s[30:31]
	s_mov_b32 m0, s81
	s_nop 0
	global_load_lds_dwordx4 v[218:219], off
	s_waitcnt vmcnt(8)
	s_waitcnt lgkmcnt(0)
	s_barrier
	s_setprio 1
	s_waitcnt lgkmcnt(0)
	v_mfma_f32_16x16x32_bf16 v[58:61], v[142:145], v[180:183], v[58:61]
	v_mfma_f32_16x16x32_bf16 v[42:45], v[142:145], v[188:191], v[42:45]
	v_mfma_f32_16x16x32_bf16 v[26:29], v[142:145], v[202:205], v[26:29]
	v_mfma_f32_16x16x32_bf16 v[10:13], v[142:145], v[210:213], v[10:13]
	v_mfma_f32_16x16x32_bf16 v[62:65], v[150:153], v[180:183], v[62:65]
	v_mfma_f32_16x16x32_bf16 v[46:49], v[150:153], v[188:191], v[46:49]
	v_mfma_f32_16x16x32_bf16 v[30:33], v[150:153], v[202:205], v[30:33]
	v_mfma_f32_16x16x32_bf16 v[14:17], v[150:153], v[210:213], v[14:17]
	v_mfma_f32_16x16x32_bf16 v[58:61], v[146:149], v[184:187], v[58:61]
	v_mfma_f32_16x16x32_bf16 v[42:45], v[146:149], v[192:195], v[42:45]
	v_mfma_f32_16x16x32_bf16 v[26:29], v[146:149], v[206:209], v[26:29]
	v_mfma_f32_16x16x32_bf16 v[10:13], v[146:149], v[214:217], v[10:13]
	v_mfma_f32_16x16x32_bf16 v[62:65], v[154:157], v[184:187], v[62:65]
	v_mfma_f32_16x16x32_bf16 v[46:49], v[154:157], v[192:195], v[46:49]
	v_mfma_f32_16x16x32_bf16 v[30:33], v[154:157], v[206:209], v[30:33]
	v_mfma_f32_16x16x32_bf16 v[14:17], v[154:157], v[214:217], v[14:17]
	s_setprio 0
	s_setprio 1
	v_mfma_f32_16x16x32_bf16 v[50:53], v[158:161], v[180:183], v[50:53]
	v_mfma_f32_16x16x32_bf16 v[34:37], v[158:161], v[188:191], v[34:37]
	v_mfma_f32_16x16x32_bf16 v[18:21], v[158:161], v[202:205], v[18:21]
	v_mfma_f32_16x16x32_bf16 v[2:5], v[158:161], v[210:213], v[2:5]
	v_mfma_f32_16x16x32_bf16 v[54:57], v[172:175], v[180:183], v[54:57]
	v_mfma_f32_16x16x32_bf16 v[38:41], v[172:175], v[188:191], v[38:41]
	v_mfma_f32_16x16x32_bf16 v[22:25], v[172:175], v[202:205], v[22:25]
	v_mfma_f32_16x16x32_bf16 v[6:9], v[172:175], v[210:213], v[6:9]
	v_mfma_f32_16x16x32_bf16 v[50:53], v[162:165], v[184:187], v[50:53]
	v_mfma_f32_16x16x32_bf16 v[34:37], v[162:165], v[192:195], v[34:37]
	v_mfma_f32_16x16x32_bf16 v[18:21], v[162:165], v[206:209], v[18:21]
	v_mfma_f32_16x16x32_bf16 v[2:5], v[162:165], v[214:217], v[2:5]
	v_mfma_f32_16x16x32_bf16 v[54:57], v[176:179], v[184:187], v[54:57]
	v_mfma_f32_16x16x32_bf16 v[38:41], v[176:179], v[192:195], v[38:41]
	v_mfma_f32_16x16x32_bf16 v[22:25], v[176:179], v[206:209], v[22:25]
	v_mfma_f32_16x16x32_bf16 v[6:9], v[176:179], v[214:217], v[6:9]
	s_setprio 0
	s_barrier
	s_add_i32 s84, s84, 2
	s_add_u32 s48, s48, 0x100
	s_addc_u32 s49, s49, 0
	s_add_u32 s53, s53, 0x100
	s_addc_u32 s69, s69, 0
	s_cmp_gt_u32 s84, 13
	s_cbranch_scc0 .LBB0_408
	s_and_b64 vcc, exec, s[64:65]
	s_cbranch_vccz .LBB0_411
	s_barrier
